# c13 + partial back-edge rotation in the six plain GEMM loops: loop counter / pointer increments and the exit compare moved ahead of the loop-back barrier (only the branch follows it); same loop length
# baseline (speedup 1.0000x reference)
.LBB0_166:
	ds_read_b128 v[144:147], v151
	ds_read_b128 v[154:157], v151 offset:1024
	ds_read_b128 v[158:161], v151 offset:2048
	ds_read_b128 v[162:165], v151 offset:3072
	ds_read_b128 v[166:169], v152
	ds_read_b128 v[170:173], v152 offset:1024
	ds_read_b128 v[174:177], v152 offset:2048
	ds_read_b128 v[178:181], v152 offset:3072
	s_add_u32 s40, s38, 0xfffc0080
	s_addc_u32 s41, s39, -1
	s_cmp_eq_u32 s66, 12
	s_cselect_b32 s43, s7, s41
	s_cselect_b32 s42, s29, s40
	s_cselect_b32 s41, s19, s65
	s_cselect_b32 s40, s61, s63
	v_lshl_add_u64 v[186:187], s[38:39], 0, v[136:137]
	s_add_i32 m0, s37, 0xc000
	ds_read_b128 v[182:185], v153
	ds_read_b128 v[190:193], v153 offset:1024
	ds_read_b128 v[194:197], v153 offset:2048
	ds_read_b128 v[198:201], v153 offset:3072
	ds_read_b128 v[202:205], v153 offset:4096
	ds_read_b128 v[206:209], v153 offset:5120
	ds_read_b128 v[210:213], v153 offset:6144
	ds_read_b128 v[214:217], v153 offset:7168
	global_load_lds_dwordx4 v[186:187], off
	v_lshl_add_u64 v[186:187], s[38:39], 0, v[138:139]
	s_add_i32 m0, s37, 0xe000
	s_nop 0
	global_load_lds_dwordx4 v[186:187], off
	s_waitcnt vmcnt(8)
	s_waitcnt lgkmcnt(0)
	s_barrier
	s_setprio 1
	s_waitcnt lgkmcnt(0)
	v_mfma_f32_16x16x32_bf16 v[124:127], v[144:147], v[182:185], v[124:127]
	v_mfma_f32_16x16x32_bf16 v[120:123], v[158:161], v[182:185], v[120:123]
	v_mfma_f32_16x16x32_bf16 v[108:111], v[144:147], v[194:197], v[108:111]
	v_mfma_f32_16x16x32_bf16 v[104:107], v[158:161], v[194:197], v[104:107]
	v_mfma_f32_16x16x32_bf16 v[92:95], v[144:147], v[202:205], v[92:95]
	v_mfma_f32_16x16x32_bf16 v[88:91], v[158:161], v[202:205], v[88:91]
	v_mfma_f32_16x16x32_bf16 v[76:79], v[144:147], v[210:213], v[76:79]
	v_mfma_f32_16x16x32_bf16 v[72:75], v[158:161], v[210:213], v[72:75]
	v_mfma_f32_16x16x32_bf16 v[124:127], v[154:157], v[190:193], v[124:127]
	v_mfma_f32_16x16x32_bf16 v[120:123], v[162:165], v[190:193], v[120:123]
	v_mfma_f32_16x16x32_bf16 v[108:111], v[154:157], v[198:201], v[108:111]
	v_mfma_f32_16x16x32_bf16 v[104:107], v[162:165], v[198:201], v[104:107]
	v_mfma_f32_16x16x32_bf16 v[92:95], v[154:157], v[206:209], v[92:95]
	v_mfma_f32_16x16x32_bf16 v[88:91], v[162:165], v[206:209], v[88:91]
	v_mfma_f32_16x16x32_bf16 v[76:79], v[154:157], v[214:217], v[76:79]
	v_mfma_f32_16x16x32_bf16 v[72:75], v[162:165], v[214:217], v[72:75]
	s_setprio 0
	s_setprio 1
	v_mfma_f32_16x16x32_bf16 v[116:119], v[166:169], v[182:185], v[116:119]
	v_mfma_f32_16x16x32_bf16 v[112:115], v[174:177], v[182:185], v[112:115]
	v_mfma_f32_16x16x32_bf16 v[100:103], v[166:169], v[194:197], v[100:103]
	v_mfma_f32_16x16x32_bf16 v[96:99], v[174:177], v[194:197], v[96:99]
	v_mfma_f32_16x16x32_bf16 v[84:87], v[166:169], v[202:205], v[84:87]
	v_mfma_f32_16x16x32_bf16 v[80:83], v[174:177], v[202:205], v[80:83]
	v_mfma_f32_16x16x32_bf16 v[68:71], v[166:169], v[210:213], v[68:71]
	v_mfma_f32_16x16x32_bf16 v[64:67], v[174:177], v[210:213], v[64:67]
	v_mfma_f32_16x16x32_bf16 v[116:119], v[170:173], v[190:193], v[116:119]
	v_mfma_f32_16x16x32_bf16 v[112:115], v[178:181], v[190:193], v[112:115]
	v_mfma_f32_16x16x32_bf16 v[100:103], v[170:173], v[198:201], v[100:103]
	v_mfma_f32_16x16x32_bf16 v[96:99], v[178:181], v[198:201], v[96:99]
	v_mfma_f32_16x16x32_bf16 v[84:87], v[170:173], v[206:209], v[84:87]
	v_mfma_f32_16x16x32_bf16 v[80:83], v[178:181], v[206:209], v[80:83]
	v_mfma_f32_16x16x32_bf16 v[68:71], v[170:173], v[214:217], v[68:71]
	v_mfma_f32_16x16x32_bf16 v[64:67], v[178:181], v[214:217], v[64:67]
	s_setprio 0
	s_barrier
	s_add_i32 s62, s58, s47
	v_lshl_add_u64 v[186:187], s[40:41], 0, v[130:131]
	s_mov_b32 m0, s62
	ds_read_b128 v[182:185], v153 offset:16384
	ds_read_b128 v[190:193], v153 offset:17408
	ds_read_b128 v[194:197], v153 offset:18432
	ds_read_b128 v[198:201], v153 offset:19456
	ds_read_b128 v[202:205], v153 offset:20480
	ds_read_b128 v[206:209], v153 offset:21504
	ds_read_b128 v[210:213], v153 offset:22528
	ds_read_b128 v[214:217], v153 offset:23552
	global_load_lds_dwordx4 v[186:187], off
	s_add_i32 m0, s62, 0x2000
	s_add_u32 s68, s40, 0x40000
	v_lshl_add_u64 v[218:219], s[40:41], 0, v[134:135]
	s_addc_u32 s69, s41, 0
	s_add_i32 s62, s59, s47
	global_load_lds_dwordx4 v[218:219], off
	v_lshl_add_u64 v[220:221], s[68:69], 0, v[130:131]
	s_mov_b32 m0, s62
	v_lshl_add_u64 v[222:223], s[42:43], 0, v[132:133]
	global_load_lds_dwordx4 v[220:221], off
	v_lshl_add_u64 v[220:221], s[68:69], 0, v[134:135]
	s_add_i32 m0, s62, 0x2000
	s_nop 0
	global_load_lds_dwordx4 v[220:221], off
	v_lshl_add_u64 v[220:221], s[42:43], 0, v[128:129]
	s_mov_b32 m0, s37
	s_nop 0
	global_load_lds_dwordx4 v[220:221], off
	s_mov_b32 m0, s48
	s_nop 0
	global_load_lds_dwordx4 v[222:223], off
	s_waitcnt vmcnt(8)
	s_waitcnt lgkmcnt(0)
	s_barrier
	s_setprio 1
	s_waitcnt lgkmcnt(0)
	v_mfma_f32_16x16x32_bf16 v[60:63], v[144:147], v[182:185], v[60:63]
	v_mfma_f32_16x16x32_bf16 v[56:59], v[158:161], v[182:185], v[56:59]
	v_mfma_f32_16x16x32_bf16 v[44:47], v[144:147], v[194:197], v[44:47]
	v_mfma_f32_16x16x32_bf16 v[40:43], v[158:161], v[194:197], v[40:43]
	v_mfma_f32_16x16x32_bf16 v[28:31], v[144:147], v[202:205], v[28:31]
	v_mfma_f32_16x16x32_bf16 v[24:27], v[158:161], v[202:205], v[24:27]
	v_mfma_f32_16x16x32_bf16 v[12:15], v[144:147], v[210:213], v[12:15]
	v_mfma_f32_16x16x32_bf16 v[8:11], v[158:161], v[210:213], v[8:11]
	v_mfma_f32_16x16x32_bf16 v[60:63], v[154:157], v[190:193], v[60:63]
	v_mfma_f32_16x16x32_bf16 v[56:59], v[162:165], v[190:193], v[56:59]
	v_mfma_f32_16x16x32_bf16 v[44:47], v[154:157], v[198:201], v[44:47]
	v_mfma_f32_16x16x32_bf16 v[40:43], v[162:165], v[198:201], v[40:43]
	v_mfma_f32_16x16x32_bf16 v[28:31], v[154:157], v[206:209], v[28:31]
	v_mfma_f32_16x16x32_bf16 v[24:27], v[162:165], v[206:209], v[24:27]
	v_mfma_f32_16x16x32_bf16 v[12:15], v[154:157], v[214:217], v[12:15]
	v_mfma_f32_16x16x32_bf16 v[8:11], v[162:165], v[214:217], v[8:11]
	s_setprio 0
	s_setprio 1
	v_mfma_f32_16x16x32_bf16 v[52:55], v[166:169], v[182:185], v[52:55]
	v_mfma_f32_16x16x32_bf16 v[48:51], v[174:177], v[182:185], v[48:51]
	v_mfma_f32_16x16x32_bf16 v[36:39], v[166:169], v[194:197], v[36:39]
	v_mfma_f32_16x16x32_bf16 v[32:35], v[174:177], v[194:197], v[32:35]
	v_mfma_f32_16x16x32_bf16 v[20:23], v[166:169], v[202:205], v[20:23]
	v_mfma_f32_16x16x32_bf16 v[16:19], v[174:177], v[202:205], v[16:19]
	v_mfma_f32_16x16x32_bf16 v[4:7], v[166:169], v[210:213], v[4:7]
	v_mfma_f32_16x16x32_bf16 v[0:3], v[174:177], v[210:213], v[0:3]
	v_mfma_f32_16x16x32_bf16 v[52:55], v[170:173], v[190:193], v[52:55]
	v_mfma_f32_16x16x32_bf16 v[48:51], v[178:181], v[190:193], v[48:51]
	v_mfma_f32_16x16x32_bf16 v[36:39], v[170:173], v[198:201], v[36:39]
	v_mfma_f32_16x16x32_bf16 v[32:35], v[178:181], v[198:201], v[32:35]
	v_mfma_f32_16x16x32_bf16 v[20:23], v[170:173], v[206:209], v[20:23]
	v_mfma_f32_16x16x32_bf16 v[16:19], v[178:181], v[206:209], v[16:19]
	v_mfma_f32_16x16x32_bf16 v[4:7], v[170:173], v[214:217], v[4:7]
	v_mfma_f32_16x16x32_bf16 v[0:3], v[178:181], v[214:217], v[0:3]
	s_setprio 0
	s_barrier
	s_add_i32 s62, 0, 0x18000
	s_add_i32 s64, 0, 0x1c000
	v_add_u32_e32 v162, s62, v149
	v_add_u32_e32 v178, s64, v149
	ds_read_b128 v[144:147], v162
	ds_read_b128 v[154:157], v162 offset:1024
	ds_read_b128 v[158:161], v162 offset:2048
	ds_read_b128 v[162:165], v162 offset:3072
	ds_read_b128 v[166:169], v178
	ds_read_b128 v[170:173], v178 offset:1024
	ds_read_b128 v[174:177], v178 offset:2048
	ds_read_b128 v[178:181], v178 offset:3072
	s_add_u32 s42, s42, 0x40000
	s_addc_u32 s43, s43, 0
	s_mov_b32 m0, s49
	v_lshl_add_u64 v[224:225], s[42:43], 0, v[128:129]
	ds_read_b128 v[182:185], v153 offset:32768
	ds_read_b128 v[190:193], v153 offset:33792
	ds_read_b128 v[194:197], v153 offset:34816
	ds_read_b128 v[198:201], v153 offset:35840
	ds_read_b128 v[202:205], v153 offset:36864
	ds_read_b128 v[206:209], v153 offset:37888
	ds_read_b128 v[210:213], v153 offset:38912
	ds_read_b128 v[214:217], v153 offset:39936
	global_load_lds_dwordx4 v[224:225], off
	v_lshl_add_u64 v[224:225], s[42:43], 0, v[132:133]
	s_mov_b32 m0, s50
	s_nop 0
	global_load_lds_dwordx4 v[224:225], off
	s_waitcnt vmcnt(8)
	s_waitcnt lgkmcnt(0)
	s_barrier
	s_setprio 1
	s_waitcnt lgkmcnt(0)
	v_mfma_f32_16x16x32_bf16 v[124:127], v[144:147], v[182:185], v[124:127]
	v_mfma_f32_16x16x32_bf16 v[120:123], v[158:161], v[182:185], v[120:123]
	v_mfma_f32_16x16x32_bf16 v[108:111], v[144:147], v[194:197], v[108:111]
	v_mfma_f32_16x16x32_bf16 v[104:107], v[158:161], v[194:197], v[104:107]
	v_mfma_f32_16x16x32_bf16 v[92:95], v[144:147], v[202:205], v[92:95]
	v_mfma_f32_16x16x32_bf16 v[88:91], v[158:161], v[202:205], v[88:91]
	v_mfma_f32_16x16x32_bf16 v[76:79], v[144:147], v[210:213], v[76:79]
	v_mfma_f32_16x16x32_bf16 v[72:75], v[158:161], v[210:213], v[72:75]
	v_mfma_f32_16x16x32_bf16 v[124:127], v[154:157], v[190:193], v[124:127]
	v_mfma_f32_16x16x32_bf16 v[120:123], v[162:165], v[190:193], v[120:123]
	v_mfma_f32_16x16x32_bf16 v[108:111], v[154:157], v[198:201], v[108:111]
	v_mfma_f32_16x16x32_bf16 v[104:107], v[162:165], v[198:201], v[104:107]
	v_mfma_f32_16x16x32_bf16 v[92:95], v[154:157], v[206:209], v[92:95]
	v_mfma_f32_16x16x32_bf16 v[88:91], v[162:165], v[206:209], v[88:91]
	v_mfma_f32_16x16x32_bf16 v[76:79], v[154:157], v[214:217], v[76:79]
	v_mfma_f32_16x16x32_bf16 v[72:75], v[162:165], v[214:217], v[72:75]
	s_setprio 0
	s_setprio 1
	v_mfma_f32_16x16x32_bf16 v[116:119], v[166:169], v[182:185], v[116:119]
	v_mfma_f32_16x16x32_bf16 v[112:115], v[174:177], v[182:185], v[112:115]
	v_mfma_f32_16x16x32_bf16 v[100:103], v[166:169], v[194:197], v[100:103]
	v_mfma_f32_16x16x32_bf16 v[96:99], v[174:177], v[194:197], v[96:99]
	v_mfma_f32_16x16x32_bf16 v[84:87], v[166:169], v[202:205], v[84:87]
	v_mfma_f32_16x16x32_bf16 v[80:83], v[174:177], v[202:205], v[80:83]
	v_mfma_f32_16x16x32_bf16 v[68:71], v[166:169], v[210:213], v[68:71]
	v_mfma_f32_16x16x32_bf16 v[64:67], v[174:177], v[210:213], v[64:67]
	v_mfma_f32_16x16x32_bf16 v[116:119], v[170:173], v[190:193], v[116:119]
	v_mfma_f32_16x16x32_bf16 v[112:115], v[178:181], v[190:193], v[112:115]
	v_mfma_f32_16x16x32_bf16 v[100:103], v[170:173], v[198:201], v[100:103]
	v_mfma_f32_16x16x32_bf16 v[96:99], v[178:181], v[198:201], v[96:99]
	v_mfma_f32_16x16x32_bf16 v[84:87], v[170:173], v[206:209], v[84:87]
	v_mfma_f32_16x16x32_bf16 v[80:83], v[178:181], v[206:209], v[80:83]
	v_mfma_f32_16x16x32_bf16 v[68:71], v[170:173], v[214:217], v[68:71]
	v_mfma_f32_16x16x32_bf16 v[64:67], v[178:181], v[214:217], v[64:67]
	s_setprio 0
	s_barrier
	s_add_i32 s42, s62, s47
	v_lshl_add_u64 v[186:187], v[186:187], 0, s[12:13]
	s_mov_b32 m0, s42
	ds_read_b128 v[182:185], v153 offset:49152
	ds_read_b128 v[190:193], v153 offset:50176
	ds_read_b128 v[194:197], v153 offset:51200
	ds_read_b128 v[198:201], v153 offset:52224
	ds_read_b128 v[202:205], v153 offset:53248
	ds_read_b128 v[206:209], v153 offset:54272
	ds_read_b128 v[210:213], v153 offset:55296
	ds_read_b128 v[214:217], v153 offset:56320
	global_load_lds_dwordx4 v[186:187], off
	s_add_i32 m0, s42, 0x2000
	s_add_u32 s40, s40, 0x40080
	v_lshl_add_u64 v[186:187], v[218:219], 0, s[12:13]
	s_addc_u32 s41, s41, 0
	s_add_i32 s42, s64, s47
	global_load_lds_dwordx4 v[186:187], off
	v_lshl_add_u64 v[186:187], s[40:41], 0, v[130:131]
	s_mov_b32 m0, s42
	s_nop 0
	global_load_lds_dwordx4 v[186:187], off
	v_lshl_add_u64 v[186:187], s[40:41], 0, v[134:135]
	s_add_i32 m0, s42, 0x2000
	s_nop 0
	global_load_lds_dwordx4 v[186:187], off
	v_lshl_add_u64 v[186:187], v[220:221], 0, s[12:13]
	s_mov_b32 m0, s52
	s_nop 0
	global_load_lds_dwordx4 v[186:187], off
	v_lshl_add_u64 v[186:187], v[222:223], 0, s[12:13]
	s_mov_b32 m0, s53
	s_nop 0
	global_load_lds_dwordx4 v[186:187], off
	s_waitcnt vmcnt(8)
	s_waitcnt lgkmcnt(0)
	s_barrier
	s_setprio 1
	s_waitcnt lgkmcnt(0)
	v_mfma_f32_16x16x32_bf16 v[60:63], v[144:147], v[182:185], v[60:63]
	v_mfma_f32_16x16x32_bf16 v[56:59], v[158:161], v[182:185], v[56:59]
	v_mfma_f32_16x16x32_bf16 v[44:47], v[144:147], v[194:197], v[44:47]
	v_mfma_f32_16x16x32_bf16 v[40:43], v[158:161], v[194:197], v[40:43]
	v_mfma_f32_16x16x32_bf16 v[28:31], v[144:147], v[202:205], v[28:31]
	v_mfma_f32_16x16x32_bf16 v[24:27], v[158:161], v[202:205], v[24:27]
	v_mfma_f32_16x16x32_bf16 v[12:15], v[144:147], v[210:213], v[12:15]
	v_mfma_f32_16x16x32_bf16 v[8:11], v[158:161], v[210:213], v[8:11]
	v_mfma_f32_16x16x32_bf16 v[60:63], v[154:157], v[190:193], v[60:63]
	v_mfma_f32_16x16x32_bf16 v[56:59], v[162:165], v[190:193], v[56:59]
	v_mfma_f32_16x16x32_bf16 v[44:47], v[154:157], v[198:201], v[44:47]
	v_mfma_f32_16x16x32_bf16 v[40:43], v[162:165], v[198:201], v[40:43]
	v_mfma_f32_16x16x32_bf16 v[28:31], v[154:157], v[206:209], v[28:31]
	v_mfma_f32_16x16x32_bf16 v[24:27], v[162:165], v[206:209], v[24:27]
	v_mfma_f32_16x16x32_bf16 v[12:15], v[154:157], v[214:217], v[12:15]
	v_mfma_f32_16x16x32_bf16 v[8:11], v[162:165], v[214:217], v[8:11]
	s_setprio 0
	s_setprio 1
	v_mfma_f32_16x16x32_bf16 v[52:55], v[166:169], v[182:185], v[52:55]
	v_mfma_f32_16x16x32_bf16 v[48:51], v[174:177], v[182:185], v[48:51]
	v_mfma_f32_16x16x32_bf16 v[36:39], v[166:169], v[194:197], v[36:39]
	v_mfma_f32_16x16x32_bf16 v[32:35], v[174:177], v[194:197], v[32:35]
	v_mfma_f32_16x16x32_bf16 v[20:23], v[166:169], v[202:205], v[20:23]
	v_mfma_f32_16x16x32_bf16 v[16:19], v[174:177], v[202:205], v[16:19]
	v_mfma_f32_16x16x32_bf16 v[4:7], v[166:169], v[210:213], v[4:7]
	v_mfma_f32_16x16x32_bf16 v[0:3], v[174:177], v[210:213], v[0:3]
	v_mfma_f32_16x16x32_bf16 v[52:55], v[170:173], v[190:193], v[52:55]
	v_mfma_f32_16x16x32_bf16 v[48:51], v[178:181], v[190:193], v[48:51]
	v_mfma_f32_16x16x32_bf16 v[36:39], v[170:173], v[198:201], v[36:39]
	v_mfma_f32_16x16x32_bf16 v[32:35], v[178:181], v[198:201], v[32:35]
	v_mfma_f32_16x16x32_bf16 v[20:23], v[170:173], v[206:209], v[20:23]
	v_mfma_f32_16x16x32_bf16 v[16:19], v[178:181], v[206:209], v[16:19]
	v_mfma_f32_16x16x32_bf16 v[4:7], v[170:173], v[214:217], v[4:7]
	v_mfma_f32_16x16x32_bf16 v[0:3], v[178:181], v[214:217], v[0:3]
	s_add_i32 s66, s66, 2
	s_add_u32 s38, s38, 0x100
	s_addc_u32 s39, s39, 0
	s_add_u32 s63, s63, 0x100
	s_addc_u32 s65, s65, 0
	s_cmp_gt_u32 s66, 13
	s_setprio 0
	s_barrier
	s_cbranch_scc0 .LBB0_166
	s_and_b64 vcc, exec, s[16:17]
	s_cbranch_vccz .LBB0_169
	s_barrier

.LBB0_550:
	ds_read_b128 v[150:153], v147
	ds_read_b128 v[154:157], v147 offset:1024
	ds_read_b128 v[158:161], v147 offset:2048
	ds_read_b128 v[162:165], v147 offset:3072
	ds_read_b128 v[166:169], v148
	ds_read_b128 v[170:173], v148 offset:1024
	ds_read_b128 v[174:177], v148 offset:2048
	ds_read_b128 v[178:181], v148 offset:3072
	s_add_u32 s50, s48, 0xfffc0080
	s_addc_u32 s51, s49, -1
	s_cmp_eq_u32 s82, 12
	s_cselect_b32 s53, s39, s51
	s_cselect_b32 s52, s78, s50
	s_cselect_b32 s51, s41, s81
	s_cselect_b32 s50, s79, s80
	v_lshl_add_u64 v[186:187], s[48:49], 0, v[136:137]
	s_add_i32 m0, s43, 0xc000
	ds_read_b128 v[182:185], v149
	ds_read_b128 v[190:193], v149 offset:1024
	ds_read_b128 v[194:197], v149 offset:2048
	ds_read_b128 v[198:201], v149 offset:3072
	ds_read_b128 v[202:205], v149 offset:4096
	ds_read_b128 v[206:209], v149 offset:5120
	ds_read_b128 v[210:213], v149 offset:6144
	ds_read_b128 v[214:217], v149 offset:7168
	global_load_lds_dwordx4 v[186:187], off
	v_lshl_add_u64 v[186:187], s[48:49], 0, v[138:139]
	s_add_i32 m0, s43, 0xe000
	s_nop 0
	global_load_lds_dwordx4 v[186:187], off
	s_waitcnt vmcnt(8)
	s_waitcnt lgkmcnt(0)
	s_barrier
	s_setprio 1
	s_waitcnt lgkmcnt(0)
	v_mfma_f32_16x16x32_bf16 v[124:127], v[150:153], v[182:185], v[124:127]
	v_mfma_f32_16x16x32_bf16 v[120:123], v[158:161], v[182:185], v[120:123]
	v_mfma_f32_16x16x32_bf16 v[116:119], v[150:153], v[194:197], v[116:119]
	v_mfma_f32_16x16x32_bf16 v[112:115], v[158:161], v[194:197], v[112:115]
	v_mfma_f32_16x16x32_bf16 v[100:103], v[150:153], v[202:205], v[100:103]
	v_mfma_f32_16x16x32_bf16 v[96:99], v[158:161], v[202:205], v[96:99]
	v_mfma_f32_16x16x32_bf16 v[84:87], v[150:153], v[210:213], v[84:87]
	v_mfma_f32_16x16x32_bf16 v[80:83], v[158:161], v[210:213], v[80:83]
	v_mfma_f32_16x16x32_bf16 v[124:127], v[154:157], v[190:193], v[124:127]
	v_mfma_f32_16x16x32_bf16 v[120:123], v[162:165], v[190:193], v[120:123]
	v_mfma_f32_16x16x32_bf16 v[116:119], v[154:157], v[198:201], v[116:119]
	v_mfma_f32_16x16x32_bf16 v[112:115], v[162:165], v[198:201], v[112:115]
	v_mfma_f32_16x16x32_bf16 v[100:103], v[154:157], v[206:209], v[100:103]
	v_mfma_f32_16x16x32_bf16 v[96:99], v[162:165], v[206:209], v[96:99]
	v_mfma_f32_16x16x32_bf16 v[84:87], v[154:157], v[214:217], v[84:87]
	v_mfma_f32_16x16x32_bf16 v[80:83], v[162:165], v[214:217], v[80:83]
	s_setprio 0
	s_setprio 1
	v_mfma_f32_16x16x32_bf16 v[108:111], v[166:169], v[182:185], v[108:111]
	v_mfma_f32_16x16x32_bf16 v[104:107], v[174:177], v[182:185], v[104:107]
	v_mfma_f32_16x16x32_bf16 v[92:95], v[166:169], v[194:197], v[92:95]
	v_mfma_f32_16x16x32_bf16 v[88:91], v[174:177], v[194:197], v[88:91]
	v_mfma_f32_16x16x32_bf16 v[76:79], v[166:169], v[202:205], v[76:79]
	v_mfma_f32_16x16x32_bf16 v[72:75], v[174:177], v[202:205], v[72:75]
	v_mfma_f32_16x16x32_bf16 v[68:71], v[166:169], v[210:213], v[68:71]
	v_mfma_f32_16x16x32_bf16 v[64:67], v[174:177], v[210:213], v[64:67]
	v_mfma_f32_16x16x32_bf16 v[108:111], v[170:173], v[190:193], v[108:111]
	v_mfma_f32_16x16x32_bf16 v[104:107], v[178:181], v[190:193], v[104:107]
	v_mfma_f32_16x16x32_bf16 v[92:95], v[170:173], v[198:201], v[92:95]
	v_mfma_f32_16x16x32_bf16 v[88:91], v[178:181], v[198:201], v[88:91]
	v_mfma_f32_16x16x32_bf16 v[76:79], v[170:173], v[206:209], v[76:79]
	v_mfma_f32_16x16x32_bf16 v[72:75], v[178:181], v[206:209], v[72:75]
	v_mfma_f32_16x16x32_bf16 v[68:71], v[170:173], v[214:217], v[68:71]
	v_mfma_f32_16x16x32_bf16 v[64:67], v[178:181], v[214:217], v[64:67]
	s_setprio 0
	s_barrier
	s_add_i32 s62, s71, s58
	v_lshl_add_u64 v[186:187], s[50:51], 0, v[132:133]
	s_mov_b32 m0, s62
	ds_read_b128 v[182:185], v149 offset:16384
	ds_read_b128 v[190:193], v149 offset:17408
	ds_read_b128 v[194:197], v149 offset:18432
	ds_read_b128 v[198:201], v149 offset:19456
	ds_read_b128 v[202:205], v149 offset:20480
	ds_read_b128 v[206:209], v149 offset:21504
	ds_read_b128 v[210:213], v149 offset:22528
	ds_read_b128 v[214:217], v149 offset:23552
	global_load_lds_dwordx4 v[186:187], off
	s_add_i32 m0, s62, 0x2000
	s_add_u32 s84, s50, 0x40000
	v_lshl_add_u64 v[218:219], s[50:51], 0, v[128:129]
	s_addc_u32 s85, s51, 0
	s_add_i32 s62, s72, s58
	global_load_lds_dwordx4 v[218:219], off
	v_lshl_add_u64 v[220:221], s[84:85], 0, v[132:133]
	s_mov_b32 m0, s62
	v_lshl_add_u64 v[222:223], s[52:53], 0, v[130:131]
	global_load_lds_dwordx4 v[220:221], off
	v_lshl_add_u64 v[220:221], s[84:85], 0, v[128:129]
	s_add_i32 m0, s62, 0x2000
	s_nop 0
	global_load_lds_dwordx4 v[220:221], off
	v_lshl_add_u64 v[220:221], s[52:53], 0, v[134:135]
	s_mov_b32 m0, s43
	s_nop 0
	global_load_lds_dwordx4 v[220:221], off
	s_mov_b32 m0, s60
	s_nop 0
	global_load_lds_dwordx4 v[222:223], off
	s_waitcnt vmcnt(8)
	s_waitcnt lgkmcnt(0)
	s_barrier
	s_setprio 1
	s_waitcnt lgkmcnt(0)
	v_mfma_f32_16x16x32_bf16 v[60:63], v[150:153], v[182:185], v[60:63]
	v_mfma_f32_16x16x32_bf16 v[56:59], v[158:161], v[182:185], v[56:59]
	v_mfma_f32_16x16x32_bf16 v[52:55], v[150:153], v[194:197], v[52:55]
	v_mfma_f32_16x16x32_bf16 v[48:51], v[158:161], v[194:197], v[48:51]
	v_mfma_f32_16x16x32_bf16 v[36:39], v[150:153], v[202:205], v[36:39]
	v_mfma_f32_16x16x32_bf16 v[32:35], v[158:161], v[202:205], v[32:35]
	v_mfma_f32_16x16x32_bf16 v[20:23], v[150:153], v[210:213], v[20:23]
	v_mfma_f32_16x16x32_bf16 v[16:19], v[158:161], v[210:213], v[16:19]
	v_mfma_f32_16x16x32_bf16 v[60:63], v[154:157], v[190:193], v[60:63]
	v_mfma_f32_16x16x32_bf16 v[56:59], v[162:165], v[190:193], v[56:59]
	v_mfma_f32_16x16x32_bf16 v[52:55], v[154:157], v[198:201], v[52:55]
	v_mfma_f32_16x16x32_bf16 v[48:51], v[162:165], v[198:201], v[48:51]
	v_mfma_f32_16x16x32_bf16 v[36:39], v[154:157], v[206:209], v[36:39]
	v_mfma_f32_16x16x32_bf16 v[32:35], v[162:165], v[206:209], v[32:35]
	v_mfma_f32_16x16x32_bf16 v[20:23], v[154:157], v[214:217], v[20:23]
	v_mfma_f32_16x16x32_bf16 v[16:19], v[162:165], v[214:217], v[16:19]
	s_setprio 0
	s_setprio 1
	v_mfma_f32_16x16x32_bf16 v[44:47], v[166:169], v[182:185], v[44:47]
	v_mfma_f32_16x16x32_bf16 v[40:43], v[174:177], v[182:185], v[40:43]
	v_mfma_f32_16x16x32_bf16 v[28:31], v[166:169], v[194:197], v[28:31]
	v_mfma_f32_16x16x32_bf16 v[24:27], v[174:177], v[194:197], v[24:27]
	v_mfma_f32_16x16x32_bf16 v[12:15], v[166:169], v[202:205], v[12:15]
	v_mfma_f32_16x16x32_bf16 v[8:11], v[174:177], v[202:205], v[8:11]
	v_mfma_f32_16x16x32_bf16 v[4:7], v[166:169], v[210:213], v[4:7]
	v_mfma_f32_16x16x32_bf16 v[0:3], v[174:177], v[210:213], v[0:3]
	v_mfma_f32_16x16x32_bf16 v[44:47], v[170:173], v[190:193], v[44:47]
	v_mfma_f32_16x16x32_bf16 v[40:43], v[178:181], v[190:193], v[40:43]
	v_mfma_f32_16x16x32_bf16 v[28:31], v[170:173], v[198:201], v[28:31]
	v_mfma_f32_16x16x32_bf16 v[24:27], v[178:181], v[198:201], v[24:27]
	v_mfma_f32_16x16x32_bf16 v[12:15], v[170:173], v[206:209], v[12:15]
	v_mfma_f32_16x16x32_bf16 v[8:11], v[178:181], v[206:209], v[8:11]
	v_mfma_f32_16x16x32_bf16 v[4:7], v[170:173], v[214:217], v[4:7]
	v_mfma_f32_16x16x32_bf16 v[0:3], v[178:181], v[214:217], v[0:3]
	s_setprio 0
	s_barrier
	s_add_i32 s62, 0, 0x18000
	s_add_i32 s64, 0, 0x1c000
	v_add_u32_e32 v162, s62, v145
	v_add_u32_e32 v178, s64, v145
	ds_read_b128 v[150:153], v162
	ds_read_b128 v[154:157], v162 offset:1024
	ds_read_b128 v[158:161], v162 offset:2048
	ds_read_b128 v[162:165], v162 offset:3072
	ds_read_b128 v[166:169], v178
	ds_read_b128 v[170:173], v178 offset:1024
	ds_read_b128 v[174:177], v178 offset:2048
	ds_read_b128 v[178:181], v178 offset:3072
	s_add_u32 s52, s52, 0x40000
	s_addc_u32 s53, s53, 0
	s_mov_b32 m0, s61
	v_lshl_add_u64 v[224:225], s[52:53], 0, v[134:135]
	ds_read_b128 v[182:185], v149 offset:32768
	ds_read_b128 v[190:193], v149 offset:33792
	ds_read_b128 v[194:197], v149 offset:34816
	ds_read_b128 v[198:201], v149 offset:35840
	ds_read_b128 v[202:205], v149 offset:36864
	ds_read_b128 v[206:209], v149 offset:37888
	ds_read_b128 v[210:213], v149 offset:38912
	ds_read_b128 v[214:217], v149 offset:39936
	global_load_lds_dwordx4 v[224:225], off
	v_lshl_add_u64 v[224:225], s[52:53], 0, v[130:131]
	s_mov_b32 m0, s63
	s_nop 0
	global_load_lds_dwordx4 v[224:225], off
	s_waitcnt vmcnt(8)
	s_waitcnt lgkmcnt(0)
	s_barrier
	s_setprio 1
	s_waitcnt lgkmcnt(0)
	v_mfma_f32_16x16x32_bf16 v[124:127], v[150:153], v[182:185], v[124:127]
	v_mfma_f32_16x16x32_bf16 v[120:123], v[158:161], v[182:185], v[120:123]
	v_mfma_f32_16x16x32_bf16 v[116:119], v[150:153], v[194:197], v[116:119]
	v_mfma_f32_16x16x32_bf16 v[112:115], v[158:161], v[194:197], v[112:115]
	v_mfma_f32_16x16x32_bf16 v[100:103], v[150:153], v[202:205], v[100:103]
	v_mfma_f32_16x16x32_bf16 v[96:99], v[158:161], v[202:205], v[96:99]
	v_mfma_f32_16x16x32_bf16 v[84:87], v[150:153], v[210:213], v[84:87]
	v_mfma_f32_16x16x32_bf16 v[80:83], v[158:161], v[210:213], v[80:83]
	v_mfma_f32_16x16x32_bf16 v[124:127], v[154:157], v[190:193], v[124:127]
	v_mfma_f32_16x16x32_bf16 v[120:123], v[162:165], v[190:193], v[120:123]
	v_mfma_f32_16x16x32_bf16 v[116:119], v[154:157], v[198:201], v[116:119]
	v_mfma_f32_16x16x32_bf16 v[112:115], v[162:165], v[198:201], v[112:115]
	v_mfma_f32_16x16x32_bf16 v[100:103], v[154:157], v[206:209], v[100:103]
	v_mfma_f32_16x16x32_bf16 v[96:99], v[162:165], v[206:209], v[96:99]
	v_mfma_f32_16x16x32_bf16 v[84:87], v[154:157], v[214:217], v[84:87]
	v_mfma_f32_16x16x32_bf16 v[80:83], v[162:165], v[214:217], v[80:83]
	s_setprio 0
	s_setprio 1
	v_mfma_f32_16x16x32_bf16 v[108:111], v[166:169], v[182:185], v[108:111]
	v_mfma_f32_16x16x32_bf16 v[104:107], v[174:177], v[182:185], v[104:107]
	v_mfma_f32_16x16x32_bf16 v[92:95], v[166:169], v[194:197], v[92:95]
	v_mfma_f32_16x16x32_bf16 v[88:91], v[174:177], v[194:197], v[88:91]
	v_mfma_f32_16x16x32_bf16 v[76:79], v[166:169], v[202:205], v[76:79]
	v_mfma_f32_16x16x32_bf16 v[72:75], v[174:177], v[202:205], v[72:75]
	v_mfma_f32_16x16x32_bf16 v[68:71], v[166:169], v[210:213], v[68:71]
	v_mfma_f32_16x16x32_bf16 v[64:67], v[174:177], v[210:213], v[64:67]
	v_mfma_f32_16x16x32_bf16 v[108:111], v[170:173], v[190:193], v[108:111]
	v_mfma_f32_16x16x32_bf16 v[104:107], v[178:181], v[190:193], v[104:107]
	v_mfma_f32_16x16x32_bf16 v[92:95], v[170:173], v[198:201], v[92:95]
	v_mfma_f32_16x16x32_bf16 v[88:91], v[178:181], v[198:201], v[88:91]
	v_mfma_f32_16x16x32_bf16 v[76:79], v[170:173], v[206:209], v[76:79]
	v_mfma_f32_16x16x32_bf16 v[72:75], v[178:181], v[206:209], v[72:75]
	v_mfma_f32_16x16x32_bf16 v[68:71], v[170:173], v[214:217], v[68:71]
	v_mfma_f32_16x16x32_bf16 v[64:67], v[178:181], v[214:217], v[64:67]
	s_setprio 0
	s_barrier
	s_add_i32 s52, s62, s58
	v_lshl_add_u64 v[186:187], v[186:187], 0, s[12:13]
	s_mov_b32 m0, s52
	ds_read_b128 v[182:185], v149 offset:49152
	ds_read_b128 v[190:193], v149 offset:50176
	ds_read_b128 v[194:197], v149 offset:51200
	ds_read_b128 v[198:201], v149 offset:52224
	ds_read_b128 v[202:205], v149 offset:53248
	ds_read_b128 v[206:209], v149 offset:54272
	ds_read_b128 v[210:213], v149 offset:55296
	ds_read_b128 v[214:217], v149 offset:56320
	global_load_lds_dwordx4 v[186:187], off
	s_add_i32 m0, s52, 0x2000
	s_add_u32 s50, s50, 0x40080
	v_lshl_add_u64 v[186:187], v[218:219], 0, s[12:13]
	s_addc_u32 s51, s51, 0
	s_add_i32 s52, s64, s58
	global_load_lds_dwordx4 v[186:187], off
	v_lshl_add_u64 v[186:187], s[50:51], 0, v[132:133]
	s_mov_b32 m0, s52
	s_nop 0
	global_load_lds_dwordx4 v[186:187], off
	v_lshl_add_u64 v[186:187], s[50:51], 0, v[128:129]
	s_add_i32 m0, s52, 0x2000
	s_nop 0
	global_load_lds_dwordx4 v[186:187], off
	v_lshl_add_u64 v[186:187], v[220:221], 0, s[12:13]
	s_mov_b32 m0, s66
	s_nop 0
	global_load_lds_dwordx4 v[186:187], off
	v_lshl_add_u64 v[186:187], v[222:223], 0, s[12:13]
	s_mov_b32 m0, s67
	s_nop 0
	global_load_lds_dwordx4 v[186:187], off
	s_waitcnt vmcnt(8)
	s_waitcnt lgkmcnt(0)
	s_barrier
	s_setprio 1
	s_waitcnt lgkmcnt(0)
	v_mfma_f32_16x16x32_bf16 v[60:63], v[150:153], v[182:185], v[60:63]
	v_mfma_f32_16x16x32_bf16 v[56:59], v[158:161], v[182:185], v[56:59]
	v_mfma_f32_16x16x32_bf16 v[52:55], v[150:153], v[194:197], v[52:55]
	v_mfma_f32_16x16x32_bf16 v[48:51], v[158:161], v[194:197], v[48:51]
	v_mfma_f32_16x16x32_bf16 v[36:39], v[150:153], v[202:205], v[36:39]
	v_mfma_f32_16x16x32_bf16 v[32:35], v[158:161], v[202:205], v[32:35]
	v_mfma_f32_16x16x32_bf16 v[20:23], v[150:153], v[210:213], v[20:23]
	v_mfma_f32_16x16x32_bf16 v[16:19], v[158:161], v[210:213], v[16:19]
	v_mfma_f32_16x16x32_bf16 v[60:63], v[154:157], v[190:193], v[60:63]
	v_mfma_f32_16x16x32_bf16 v[56:59], v[162:165], v[190:193], v[56:59]
	v_mfma_f32_16x16x32_bf16 v[52:55], v[154:157], v[198:201], v[52:55]
	v_mfma_f32_16x16x32_bf16 v[48:51], v[162:165], v[198:201], v[48:51]
	v_mfma_f32_16x16x32_bf16 v[36:39], v[154:157], v[206:209], v[36:39]
	v_mfma_f32_16x16x32_bf16 v[32:35], v[162:165], v[206:209], v[32:35]
	v_mfma_f32_16x16x32_bf16 v[20:23], v[154:157], v[214:217], v[20:23]
	v_mfma_f32_16x16x32_bf16 v[16:19], v[162:165], v[214:217], v[16:19]
	s_setprio 0
	s_setprio 1
	v_mfma_f32_16x16x32_bf16 v[44:47], v[166:169], v[182:185], v[44:47]
	v_mfma_f32_16x16x32_bf16 v[40:43], v[174:177], v[182:185], v[40:43]
	v_mfma_f32_16x16x32_bf16 v[28:31], v[166:169], v[194:197], v[28:31]
	v_mfma_f32_16x16x32_bf16 v[24:27], v[174:177], v[194:197], v[24:27]
	v_mfma_f32_16x16x32_bf16 v[12:15], v[166:169], v[202:205], v[12:15]
	v_mfma_f32_16x16x32_bf16 v[8:11], v[174:177], v[202:205], v[8:11]
	v_mfma_f32_16x16x32_bf16 v[4:7], v[166:169], v[210:213], v[4:7]
	v_mfma_f32_16x16x32_bf16 v[0:3], v[174:177], v[210:213], v[0:3]
	v_mfma_f32_16x16x32_bf16 v[44:47], v[170:173], v[190:193], v[44:47]
	v_mfma_f32_16x16x32_bf16 v[40:43], v[178:181], v[190:193], v[40:43]
	v_mfma_f32_16x16x32_bf16 v[28:31], v[170:173], v[198:201], v[28:31]
	v_mfma_f32_16x16x32_bf16 v[24:27], v[178:181], v[198:201], v[24:27]
	v_mfma_f32_16x16x32_bf16 v[12:15], v[170:173], v[206:209], v[12:15]
	v_mfma_f32_16x16x32_bf16 v[8:11], v[178:181], v[206:209], v[8:11]
	v_mfma_f32_16x16x32_bf16 v[4:7], v[170:173], v[214:217], v[4:7]
	v_mfma_f32_16x16x32_bf16 v[0:3], v[178:181], v[214:217], v[0:3]
	s_add_i32 s82, s82, 2
	s_add_u32 s48, s48, 0x100
	s_addc_u32 s49, s49, 0
	s_add_u32 s80, s80, 0x100
	s_addc_u32 s81, s81, 0
	s_cmp_gt_u32 s82, 13
	s_setprio 0
	s_barrier
	s_cbranch_scc0 .LBB0_550
	s_and_b64 vcc, exec, s[16:17]
	s_cbranch_vccz .LBB0_553
	s_barrier

.LBB0_679:
	ds_read_b128 v[152:155], v149
	ds_read_b128 v[156:159], v149 offset:1024
	ds_read_b128 v[160:163], v149 offset:2048
	ds_read_b128 v[164:167], v149 offset:3072
	ds_read_b128 v[168:171], v150
	ds_read_b128 v[172:175], v150 offset:1024
	ds_read_b128 v[176:179], v150 offset:2048
	ds_read_b128 v[180:183], v150 offset:3072
	s_add_u32 s50, s48, 0xfffc0080
	s_addc_u32 s51, s49, -1
	s_cmp_eq_u32 s83, 12
	s_cselect_b32 s53, s41, s51
	s_cselect_b32 s52, s79, s50
	s_cselect_b32 s51, s39, s82
	s_cselect_b32 s50, s80, s81
	v_lshl_add_u64 v[144:145], s[48:49], 0, v[136:137]
	s_add_i32 m0, s47, 0xc000
	ds_read_b128 v[184:187], v151
	ds_read_b128 v[190:193], v151 offset:1024
	ds_read_b128 v[194:197], v151 offset:2048
	ds_read_b128 v[198:201], v151 offset:3072
	ds_read_b128 v[202:205], v151 offset:4096
	ds_read_b128 v[206:209], v151 offset:5120
	ds_read_b128 v[210:213], v151 offset:6144
	ds_read_b128 v[214:217], v151 offset:7168
	global_load_lds_dwordx4 v[144:145], off
	v_lshl_add_u64 v[144:145], s[48:49], 0, v[138:139]
	s_add_i32 m0, s47, 0xe000
	s_nop 0
	global_load_lds_dwordx4 v[144:145], off
	s_waitcnt vmcnt(8)
	s_waitcnt lgkmcnt(0)
	s_barrier
	s_setprio 1
	s_waitcnt lgkmcnt(0)
	v_mfma_f32_16x16x32_bf16 v[124:127], v[152:155], v[184:187], v[124:127]
	v_mfma_f32_16x16x32_bf16 v[120:123], v[160:163], v[184:187], v[120:123]
	v_mfma_f32_16x16x32_bf16 v[108:111], v[152:155], v[194:197], v[108:111]
	v_mfma_f32_16x16x32_bf16 v[104:107], v[160:163], v[194:197], v[104:107]
	v_mfma_f32_16x16x32_bf16 v[92:95], v[152:155], v[202:205], v[92:95]
	v_mfma_f32_16x16x32_bf16 v[88:91], v[160:163], v[202:205], v[88:91]
	v_mfma_f32_16x16x32_bf16 v[76:79], v[152:155], v[210:213], v[76:79]
	v_mfma_f32_16x16x32_bf16 v[72:75], v[160:163], v[210:213], v[72:75]
	v_mfma_f32_16x16x32_bf16 v[124:127], v[156:159], v[190:193], v[124:127]
	v_mfma_f32_16x16x32_bf16 v[120:123], v[164:167], v[190:193], v[120:123]
	v_mfma_f32_16x16x32_bf16 v[108:111], v[156:159], v[198:201], v[108:111]
	v_mfma_f32_16x16x32_bf16 v[104:107], v[164:167], v[198:201], v[104:107]
	v_mfma_f32_16x16x32_bf16 v[92:95], v[156:159], v[206:209], v[92:95]
	v_mfma_f32_16x16x32_bf16 v[88:91], v[164:167], v[206:209], v[88:91]
	v_mfma_f32_16x16x32_bf16 v[76:79], v[156:159], v[214:217], v[76:79]
	v_mfma_f32_16x16x32_bf16 v[72:75], v[164:167], v[214:217], v[72:75]
	s_setprio 0
	s_setprio 1
	v_mfma_f32_16x16x32_bf16 v[116:119], v[168:171], v[184:187], v[116:119]
	v_mfma_f32_16x16x32_bf16 v[112:115], v[176:179], v[184:187], v[112:115]
	v_mfma_f32_16x16x32_bf16 v[100:103], v[168:171], v[194:197], v[100:103]
	v_mfma_f32_16x16x32_bf16 v[96:99], v[176:179], v[194:197], v[96:99]
	v_mfma_f32_16x16x32_bf16 v[84:87], v[168:171], v[202:205], v[84:87]
	v_mfma_f32_16x16x32_bf16 v[80:83], v[176:179], v[202:205], v[80:83]
	v_mfma_f32_16x16x32_bf16 v[68:71], v[168:171], v[210:213], v[68:71]
	v_mfma_f32_16x16x32_bf16 v[64:67], v[176:179], v[210:213], v[64:67]
	v_mfma_f32_16x16x32_bf16 v[116:119], v[172:175], v[190:193], v[116:119]
	v_mfma_f32_16x16x32_bf16 v[112:115], v[180:183], v[190:193], v[112:115]
	v_mfma_f32_16x16x32_bf16 v[100:103], v[172:175], v[198:201], v[100:103]
	v_mfma_f32_16x16x32_bf16 v[96:99], v[180:183], v[198:201], v[96:99]
	v_mfma_f32_16x16x32_bf16 v[84:87], v[172:175], v[206:209], v[84:87]
	v_mfma_f32_16x16x32_bf16 v[80:83], v[180:183], v[206:209], v[80:83]
	v_mfma_f32_16x16x32_bf16 v[68:71], v[172:175], v[214:217], v[68:71]
	v_mfma_f32_16x16x32_bf16 v[64:67], v[180:183], v[214:217], v[64:67]
	s_setprio 0
	s_barrier
	s_add_i32 s62, s72, s58
	v_lshl_add_u64 v[144:145], s[50:51], 0, v[132:133]
	s_mov_b32 m0, s62
	ds_read_b128 v[184:187], v151 offset:16384
	ds_read_b128 v[190:193], v151 offset:17408
	ds_read_b128 v[194:197], v151 offset:18432
	ds_read_b128 v[198:201], v151 offset:19456
	ds_read_b128 v[202:205], v151 offset:20480
	ds_read_b128 v[206:209], v151 offset:21504
	ds_read_b128 v[210:213], v151 offset:22528
	ds_read_b128 v[214:217], v151 offset:23552
	global_load_lds_dwordx4 v[144:145], off
	s_add_i32 m0, s62, 0x2000
	s_add_u32 s84, s50, 0x40000
	v_lshl_add_u64 v[218:219], s[50:51], 0, v[128:129]
	s_addc_u32 s85, s51, 0
	s_add_i32 s62, s73, s58
	global_load_lds_dwordx4 v[218:219], off
	v_lshl_add_u64 v[220:221], s[84:85], 0, v[132:133]
	s_mov_b32 m0, s62
	v_lshl_add_u64 v[222:223], s[52:53], 0, v[130:131]
	global_load_lds_dwordx4 v[220:221], off
	v_lshl_add_u64 v[220:221], s[84:85], 0, v[128:129]
	s_add_i32 m0, s62, 0x2000
	s_nop 0
	global_load_lds_dwordx4 v[220:221], off
	v_lshl_add_u64 v[220:221], s[52:53], 0, v[134:135]
	s_mov_b32 m0, s47
	s_nop 0
	global_load_lds_dwordx4 v[220:221], off
	s_mov_b32 m0, s61
	s_nop 0
	global_load_lds_dwordx4 v[222:223], off
	s_waitcnt vmcnt(8)
	s_waitcnt lgkmcnt(0)
	s_barrier
	s_setprio 1
	s_waitcnt lgkmcnt(0)
	v_mfma_f32_16x16x32_bf16 v[60:63], v[152:155], v[184:187], v[60:63]
	v_mfma_f32_16x16x32_bf16 v[56:59], v[160:163], v[184:187], v[56:59]
	v_mfma_f32_16x16x32_bf16 v[44:47], v[152:155], v[194:197], v[44:47]
	v_mfma_f32_16x16x32_bf16 v[40:43], v[160:163], v[194:197], v[40:43]
	v_mfma_f32_16x16x32_bf16 v[28:31], v[152:155], v[202:205], v[28:31]
	v_mfma_f32_16x16x32_bf16 v[24:27], v[160:163], v[202:205], v[24:27]
	v_mfma_f32_16x16x32_bf16 v[12:15], v[152:155], v[210:213], v[12:15]
	v_mfma_f32_16x16x32_bf16 v[8:11], v[160:163], v[210:213], v[8:11]
	v_mfma_f32_16x16x32_bf16 v[60:63], v[156:159], v[190:193], v[60:63]
	v_mfma_f32_16x16x32_bf16 v[56:59], v[164:167], v[190:193], v[56:59]
	v_mfma_f32_16x16x32_bf16 v[44:47], v[156:159], v[198:201], v[44:47]
	v_mfma_f32_16x16x32_bf16 v[40:43], v[164:167], v[198:201], v[40:43]
	v_mfma_f32_16x16x32_bf16 v[28:31], v[156:159], v[206:209], v[28:31]
	v_mfma_f32_16x16x32_bf16 v[24:27], v[164:167], v[206:209], v[24:27]
	v_mfma_f32_16x16x32_bf16 v[12:15], v[156:159], v[214:217], v[12:15]
	v_mfma_f32_16x16x32_bf16 v[8:11], v[164:167], v[214:217], v[8:11]
	s_setprio 0
	s_setprio 1
	v_mfma_f32_16x16x32_bf16 v[52:55], v[168:171], v[184:187], v[52:55]
	v_mfma_f32_16x16x32_bf16 v[48:51], v[176:179], v[184:187], v[48:51]
	v_mfma_f32_16x16x32_bf16 v[36:39], v[168:171], v[194:197], v[36:39]
	v_mfma_f32_16x16x32_bf16 v[32:35], v[176:179], v[194:197], v[32:35]
	v_mfma_f32_16x16x32_bf16 v[20:23], v[168:171], v[202:205], v[20:23]
	v_mfma_f32_16x16x32_bf16 v[16:19], v[176:179], v[202:205], v[16:19]
	v_mfma_f32_16x16x32_bf16 v[4:7], v[168:171], v[210:213], v[4:7]
	v_mfma_f32_16x16x32_bf16 v[0:3], v[176:179], v[210:213], v[0:3]
	v_mfma_f32_16x16x32_bf16 v[52:55], v[172:175], v[190:193], v[52:55]
	v_mfma_f32_16x16x32_bf16 v[48:51], v[180:183], v[190:193], v[48:51]
	v_mfma_f32_16x16x32_bf16 v[36:39], v[172:175], v[198:201], v[36:39]
	v_mfma_f32_16x16x32_bf16 v[32:35], v[180:183], v[198:201], v[32:35]
	v_mfma_f32_16x16x32_bf16 v[20:23], v[172:175], v[206:209], v[20:23]
	v_mfma_f32_16x16x32_bf16 v[16:19], v[180:183], v[206:209], v[16:19]
	v_mfma_f32_16x16x32_bf16 v[4:7], v[172:175], v[214:217], v[4:7]
	v_mfma_f32_16x16x32_bf16 v[0:3], v[180:183], v[214:217], v[0:3]
	s_setprio 0
	s_barrier
	s_add_i32 s62, 0, 0x18000
	s_add_i32 s64, 0, 0x1c000
	v_add_u32_e32 v164, s62, v147
	v_add_u32_e32 v180, s64, v147
	ds_read_b128 v[152:155], v164
	ds_read_b128 v[156:159], v164 offset:1024
	ds_read_b128 v[160:163], v164 offset:2048
	ds_read_b128 v[164:167], v164 offset:3072
	ds_read_b128 v[168:171], v180
	ds_read_b128 v[172:175], v180 offset:1024
	ds_read_b128 v[176:179], v180 offset:2048
	ds_read_b128 v[180:183], v180 offset:3072
	s_add_u32 s52, s52, 0x40000
	s_addc_u32 s53, s53, 0
	s_mov_b32 m0, s63
	v_lshl_add_u64 v[224:225], s[52:53], 0, v[134:135]
	ds_read_b128 v[184:187], v151 offset:32768
	ds_read_b128 v[190:193], v151 offset:33792
	ds_read_b128 v[194:197], v151 offset:34816
	ds_read_b128 v[198:201], v151 offset:35840
	ds_read_b128 v[202:205], v151 offset:36864
	ds_read_b128 v[206:209], v151 offset:37888
	ds_read_b128 v[210:213], v151 offset:38912
	ds_read_b128 v[214:217], v151 offset:39936
	global_load_lds_dwordx4 v[224:225], off
	v_lshl_add_u64 v[224:225], s[52:53], 0, v[130:131]
	s_mov_b32 m0, s66
	s_nop 0
	global_load_lds_dwordx4 v[224:225], off
	s_waitcnt vmcnt(8)
	s_waitcnt lgkmcnt(0)
	s_barrier
	s_setprio 1
	s_waitcnt lgkmcnt(0)
	v_mfma_f32_16x16x32_bf16 v[124:127], v[152:155], v[184:187], v[124:127]
	v_mfma_f32_16x16x32_bf16 v[120:123], v[160:163], v[184:187], v[120:123]
	v_mfma_f32_16x16x32_bf16 v[108:111], v[152:155], v[194:197], v[108:111]
	v_mfma_f32_16x16x32_bf16 v[104:107], v[160:163], v[194:197], v[104:107]
	v_mfma_f32_16x16x32_bf16 v[92:95], v[152:155], v[202:205], v[92:95]
	v_mfma_f32_16x16x32_bf16 v[88:91], v[160:163], v[202:205], v[88:91]
	v_mfma_f32_16x16x32_bf16 v[76:79], v[152:155], v[210:213], v[76:79]
	v_mfma_f32_16x16x32_bf16 v[72:75], v[160:163], v[210:213], v[72:75]
	v_mfma_f32_16x16x32_bf16 v[124:127], v[156:159], v[190:193], v[124:127]
	v_mfma_f32_16x16x32_bf16 v[120:123], v[164:167], v[190:193], v[120:123]
	v_mfma_f32_16x16x32_bf16 v[108:111], v[156:159], v[198:201], v[108:111]
	v_mfma_f32_16x16x32_bf16 v[104:107], v[164:167], v[198:201], v[104:107]
	v_mfma_f32_16x16x32_bf16 v[92:95], v[156:159], v[206:209], v[92:95]
	v_mfma_f32_16x16x32_bf16 v[88:91], v[164:167], v[206:209], v[88:91]
	v_mfma_f32_16x16x32_bf16 v[76:79], v[156:159], v[214:217], v[76:79]
	v_mfma_f32_16x16x32_bf16 v[72:75], v[164:167], v[214:217], v[72:75]
	s_setprio 0
	s_setprio 1
	v_mfma_f32_16x16x32_bf16 v[116:119], v[168:171], v[184:187], v[116:119]
	v_mfma_f32_16x16x32_bf16 v[112:115], v[176:179], v[184:187], v[112:115]
	v_mfma_f32_16x16x32_bf16 v[100:103], v[168:171], v[194:197], v[100:103]
	v_mfma_f32_16x16x32_bf16 v[96:99], v[176:179], v[194:197], v[96:99]
	v_mfma_f32_16x16x32_bf16 v[84:87], v[168:171], v[202:205], v[84:87]
	v_mfma_f32_16x16x32_bf16 v[80:83], v[176:179], v[202:205], v[80:83]
	v_mfma_f32_16x16x32_bf16 v[68:71], v[168:171], v[210:213], v[68:71]
	v_mfma_f32_16x16x32_bf16 v[64:67], v[176:179], v[210:213], v[64:67]
	v_mfma_f32_16x16x32_bf16 v[116:119], v[172:175], v[190:193], v[116:119]
	v_mfma_f32_16x16x32_bf16 v[112:115], v[180:183], v[190:193], v[112:115]
	v_mfma_f32_16x16x32_bf16 v[100:103], v[172:175], v[198:201], v[100:103]
	v_mfma_f32_16x16x32_bf16 v[96:99], v[180:183], v[198:201], v[96:99]
	v_mfma_f32_16x16x32_bf16 v[84:87], v[172:175], v[206:209], v[84:87]
	v_mfma_f32_16x16x32_bf16 v[80:83], v[180:183], v[206:209], v[80:83]
	v_mfma_f32_16x16x32_bf16 v[68:71], v[172:175], v[214:217], v[68:71]
	v_mfma_f32_16x16x32_bf16 v[64:67], v[180:183], v[214:217], v[64:67]
	s_setprio 0
	s_barrier
	s_add_i32 s52, s62, s58
	v_lshl_add_u64 v[144:145], v[144:145], 0, s[10:11]
	s_mov_b32 m0, s52
	ds_read_b128 v[184:187], v151 offset:49152
	ds_read_b128 v[190:193], v151 offset:50176
	ds_read_b128 v[194:197], v151 offset:51200
	ds_read_b128 v[198:201], v151 offset:52224
	ds_read_b128 v[202:205], v151 offset:53248
	ds_read_b128 v[206:209], v151 offset:54272
	ds_read_b128 v[210:213], v151 offset:55296
	ds_read_b128 v[214:217], v151 offset:56320
	global_load_lds_dwordx4 v[144:145], off
	s_add_i32 m0, s52, 0x2000
	s_add_u32 s50, s50, 0x40080
	v_lshl_add_u64 v[144:145], v[218:219], 0, s[10:11]
	s_addc_u32 s51, s51, 0
	s_add_i32 s52, s64, s58
	global_load_lds_dwordx4 v[144:145], off
	v_lshl_add_u64 v[144:145], s[50:51], 0, v[132:133]
	s_mov_b32 m0, s52
	s_nop 0
	global_load_lds_dwordx4 v[144:145], off
	v_lshl_add_u64 v[144:145], s[50:51], 0, v[128:129]
	s_add_i32 m0, s52, 0x2000
	s_nop 0
	global_load_lds_dwordx4 v[144:145], off
	v_lshl_add_u64 v[144:145], v[220:221], 0, s[10:11]
	s_mov_b32 m0, s67
	s_nop 0
	global_load_lds_dwordx4 v[144:145], off
	v_lshl_add_u64 v[144:145], v[222:223], 0, s[10:11]
	s_mov_b32 m0, s68
	s_nop 0
	global_load_lds_dwordx4 v[144:145], off
	s_waitcnt vmcnt(8)
	s_waitcnt lgkmcnt(0)
	s_barrier
	s_setprio 1
	s_waitcnt lgkmcnt(0)
	v_mfma_f32_16x16x32_bf16 v[60:63], v[152:155], v[184:187], v[60:63]
	v_mfma_f32_16x16x32_bf16 v[56:59], v[160:163], v[184:187], v[56:59]
	v_mfma_f32_16x16x32_bf16 v[44:47], v[152:155], v[194:197], v[44:47]
	v_mfma_f32_16x16x32_bf16 v[40:43], v[160:163], v[194:197], v[40:43]
	v_mfma_f32_16x16x32_bf16 v[28:31], v[152:155], v[202:205], v[28:31]
	v_mfma_f32_16x16x32_bf16 v[24:27], v[160:163], v[202:205], v[24:27]
	v_mfma_f32_16x16x32_bf16 v[12:15], v[152:155], v[210:213], v[12:15]
	v_mfma_f32_16x16x32_bf16 v[8:11], v[160:163], v[210:213], v[8:11]
	v_mfma_f32_16x16x32_bf16 v[60:63], v[156:159], v[190:193], v[60:63]
	v_mfma_f32_16x16x32_bf16 v[56:59], v[164:167], v[190:193], v[56:59]
	v_mfma_f32_16x16x32_bf16 v[44:47], v[156:159], v[198:201], v[44:47]
	v_mfma_f32_16x16x32_bf16 v[40:43], v[164:167], v[198:201], v[40:43]
	v_mfma_f32_16x16x32_bf16 v[28:31], v[156:159], v[206:209], v[28:31]
	v_mfma_f32_16x16x32_bf16 v[24:27], v[164:167], v[206:209], v[24:27]
	v_mfma_f32_16x16x32_bf16 v[12:15], v[156:159], v[214:217], v[12:15]
	v_mfma_f32_16x16x32_bf16 v[8:11], v[164:167], v[214:217], v[8:11]
	s_setprio 0
	s_setprio 1
	v_mfma_f32_16x16x32_bf16 v[52:55], v[168:171], v[184:187], v[52:55]
	v_mfma_f32_16x16x32_bf16 v[48:51], v[176:179], v[184:187], v[48:51]
	v_mfma_f32_16x16x32_bf16 v[36:39], v[168:171], v[194:197], v[36:39]
	v_mfma_f32_16x16x32_bf16 v[32:35], v[176:179], v[194:197], v[32:35]
	v_mfma_f32_16x16x32_bf16 v[20:23], v[168:171], v[202:205], v[20:23]
	v_mfma_f32_16x16x32_bf16 v[16:19], v[176:179], v[202:205], v[16:19]
	v_mfma_f32_16x16x32_bf16 v[4:7], v[168:171], v[210:213], v[4:7]
	v_mfma_f32_16x16x32_bf16 v[0:3], v[176:179], v[210:213], v[0:3]
	v_mfma_f32_16x16x32_bf16 v[52:55], v[172:175], v[190:193], v[52:55]
	v_mfma_f32_16x16x32_bf16 v[48:51], v[180:183], v[190:193], v[48:51]
	v_mfma_f32_16x16x32_bf16 v[36:39], v[172:175], v[198:201], v[36:39]
	v_mfma_f32_16x16x32_bf16 v[32:35], v[180:183], v[198:201], v[32:35]
	v_mfma_f32_16x16x32_bf16 v[20:23], v[172:175], v[206:209], v[20:23]
	v_mfma_f32_16x16x32_bf16 v[16:19], v[180:183], v[206:209], v[16:19]
	v_mfma_f32_16x16x32_bf16 v[4:7], v[172:175], v[214:217], v[4:7]
	v_mfma_f32_16x16x32_bf16 v[0:3], v[180:183], v[214:217], v[0:3]
	s_add_i32 s83, s83, 2
	s_add_u32 s48, s48, 0x100
	s_addc_u32 s49, s49, 0
	s_add_u32 s81, s81, 0x100
	s_addc_u32 s82, s82, 0
	s_cmp_gt_u32 s83, 13
	s_setprio 0
	s_barrier
	s_cbranch_scc0 .LBB0_679
	s_and_b64 vcc, exec, s[12:13]
	s_cbranch_vccz .LBB0_682
	s_barrier

.LBB0_881:
	ds_read_b128 v[144:147], v175
	ds_read_b128 v[148:151], v175 offset:1024
	ds_read_b128 v[152:155], v175 offset:2048
	ds_read_b128 v[156:159], v175 offset:3072
	ds_read_b128 v[160:163], v176
	ds_read_b128 v[164:167], v176 offset:1024
	ds_read_b128 v[168:171], v176 offset:2048
	ds_read_b128 v[178:181], v176 offset:3072
	s_add_u32 s50, s48, 0xfffc0080
	s_addc_u32 s51, s49, -1
	s_cmp_eq_u32 s78, 12
	s_cselect_b32 s53, s7, s51
	s_cselect_b32 s52, s9, s50
	s_cselect_b32 s51, s41, s77
	s_cselect_b32 s50, s43, s63
	v_lshl_add_u64 v[186:187], s[48:49], 0, v[136:137]
	s_add_i32 m0, s59, 0xc000
	ds_read_b128 v[182:185], v177
	ds_read_b128 v[190:193], v177 offset:1024
	ds_read_b128 v[194:197], v177 offset:2048
	ds_read_b128 v[198:201], v177 offset:3072
	ds_read_b128 v[202:205], v177 offset:4096
	ds_read_b128 v[206:209], v177 offset:5120
	ds_read_b128 v[210:213], v177 offset:6144
	ds_read_b128 v[214:217], v177 offset:7168
	global_load_lds_dwordx4 v[186:187], off
	v_lshl_add_u64 v[186:187], s[48:49], 0, v[138:139]
	s_add_i32 m0, s59, 0xe000
	s_nop 0
	global_load_lds_dwordx4 v[186:187], off
	s_waitcnt vmcnt(8)
	s_waitcnt lgkmcnt(0)
	s_barrier
	s_setprio 1
	s_waitcnt lgkmcnt(0)
	v_mfma_f32_16x16x32_bf16 v[124:127], v[144:147], v[182:185], v[124:127]
	v_mfma_f32_16x16x32_bf16 v[120:123], v[152:155], v[182:185], v[120:123]
	v_mfma_f32_16x16x32_bf16 v[108:111], v[144:147], v[194:197], v[108:111]
	v_mfma_f32_16x16x32_bf16 v[104:107], v[152:155], v[194:197], v[104:107]
	v_mfma_f32_16x16x32_bf16 v[92:95], v[144:147], v[202:205], v[92:95]
	v_mfma_f32_16x16x32_bf16 v[88:91], v[152:155], v[202:205], v[88:91]
	v_mfma_f32_16x16x32_bf16 v[76:79], v[144:147], v[210:213], v[76:79]
	v_mfma_f32_16x16x32_bf16 v[72:75], v[152:155], v[210:213], v[72:75]
	v_mfma_f32_16x16x32_bf16 v[124:127], v[148:151], v[190:193], v[124:127]
	v_mfma_f32_16x16x32_bf16 v[120:123], v[156:159], v[190:193], v[120:123]
	v_mfma_f32_16x16x32_bf16 v[108:111], v[148:151], v[198:201], v[108:111]
	v_mfma_f32_16x16x32_bf16 v[104:107], v[156:159], v[198:201], v[104:107]
	v_mfma_f32_16x16x32_bf16 v[92:95], v[148:151], v[206:209], v[92:95]
	v_mfma_f32_16x16x32_bf16 v[88:91], v[156:159], v[206:209], v[88:91]
	v_mfma_f32_16x16x32_bf16 v[76:79], v[148:151], v[214:217], v[76:79]
	v_mfma_f32_16x16x32_bf16 v[72:75], v[156:159], v[214:217], v[72:75]
	s_setprio 0
	s_setprio 1
	v_mfma_f32_16x16x32_bf16 v[116:119], v[160:163], v[182:185], v[116:119]
	v_mfma_f32_16x16x32_bf16 v[112:115], v[168:171], v[182:185], v[112:115]
	v_mfma_f32_16x16x32_bf16 v[100:103], v[160:163], v[194:197], v[100:103]
	v_mfma_f32_16x16x32_bf16 v[96:99], v[168:171], v[194:197], v[96:99]
	v_mfma_f32_16x16x32_bf16 v[84:87], v[160:163], v[202:205], v[84:87]
	v_mfma_f32_16x16x32_bf16 v[80:83], v[168:171], v[202:205], v[80:83]
	v_mfma_f32_16x16x32_bf16 v[68:71], v[160:163], v[210:213], v[68:71]
	v_mfma_f32_16x16x32_bf16 v[64:67], v[168:171], v[210:213], v[64:67]
	v_mfma_f32_16x16x32_bf16 v[116:119], v[164:167], v[190:193], v[116:119]
	v_mfma_f32_16x16x32_bf16 v[112:115], v[178:181], v[190:193], v[112:115]
	v_mfma_f32_16x16x32_bf16 v[100:103], v[164:167], v[198:201], v[100:103]
	v_mfma_f32_16x16x32_bf16 v[96:99], v[178:181], v[198:201], v[96:99]
	v_mfma_f32_16x16x32_bf16 v[84:87], v[164:167], v[206:209], v[84:87]
	v_mfma_f32_16x16x32_bf16 v[80:83], v[178:181], v[206:209], v[80:83]
	v_mfma_f32_16x16x32_bf16 v[68:71], v[164:167], v[214:217], v[68:71]
	v_mfma_f32_16x16x32_bf16 v[64:67], v[178:181], v[214:217], v[64:67]
	s_setprio 0
	s_barrier
	s_add_i32 s62, s74, s58
	v_lshl_add_u64 v[186:187], s[50:51], 0, v[130:131]
	s_mov_b32 m0, s62
	ds_read_b128 v[182:185], v177 offset:16384
	ds_read_b128 v[190:193], v177 offset:17408
	ds_read_b128 v[194:197], v177 offset:18432
	ds_read_b128 v[198:201], v177 offset:19456
	ds_read_b128 v[202:205], v177 offset:20480
	ds_read_b128 v[206:209], v177 offset:21504
	ds_read_b128 v[210:213], v177 offset:22528
	ds_read_b128 v[214:217], v177 offset:23552
	global_load_lds_dwordx4 v[186:187], off
	s_add_i32 m0, s62, 0x2000
	s_add_u32 s80, s50, 0x40000
	v_lshl_add_u64 v[218:219], s[50:51], 0, v[134:135]
	s_addc_u32 s81, s51, 0
	s_add_i32 s62, s75, s58
	global_load_lds_dwordx4 v[218:219], off
	v_lshl_add_u64 v[220:221], s[80:81], 0, v[130:131]
	s_mov_b32 m0, s62
	v_lshl_add_u64 v[222:223], s[52:53], 0, v[132:133]
	global_load_lds_dwordx4 v[220:221], off
	v_lshl_add_u64 v[220:221], s[80:81], 0, v[134:135]
	s_add_i32 m0, s62, 0x2000
	s_nop 0
	global_load_lds_dwordx4 v[220:221], off
	v_lshl_add_u64 v[220:221], s[52:53], 0, v[128:129]
	s_mov_b32 m0, s59
	s_nop 0
	global_load_lds_dwordx4 v[220:221], off
	s_mov_b32 m0, s60
	s_nop 0
	global_load_lds_dwordx4 v[222:223], off
	s_waitcnt vmcnt(8)
	s_waitcnt lgkmcnt(0)
	s_barrier
	s_setprio 1
	s_waitcnt lgkmcnt(0)
	v_mfma_f32_16x16x32_bf16 v[60:63], v[144:147], v[182:185], v[60:63]
	v_mfma_f32_16x16x32_bf16 v[56:59], v[152:155], v[182:185], v[56:59]
	v_mfma_f32_16x16x32_bf16 v[44:47], v[144:147], v[194:197], v[44:47]
	v_mfma_f32_16x16x32_bf16 v[40:43], v[152:155], v[194:197], v[40:43]
	v_mfma_f32_16x16x32_bf16 v[28:31], v[144:147], v[202:205], v[28:31]
	v_mfma_f32_16x16x32_bf16 v[24:27], v[152:155], v[202:205], v[24:27]
	v_mfma_f32_16x16x32_bf16 v[12:15], v[144:147], v[210:213], v[12:15]
	v_mfma_f32_16x16x32_bf16 v[8:11], v[152:155], v[210:213], v[8:11]
	v_mfma_f32_16x16x32_bf16 v[60:63], v[148:151], v[190:193], v[60:63]
	v_mfma_f32_16x16x32_bf16 v[56:59], v[156:159], v[190:193], v[56:59]
	v_mfma_f32_16x16x32_bf16 v[44:47], v[148:151], v[198:201], v[44:47]
	v_mfma_f32_16x16x32_bf16 v[40:43], v[156:159], v[198:201], v[40:43]
	v_mfma_f32_16x16x32_bf16 v[28:31], v[148:151], v[206:209], v[28:31]
	v_mfma_f32_16x16x32_bf16 v[24:27], v[156:159], v[206:209], v[24:27]
	v_mfma_f32_16x16x32_bf16 v[12:15], v[148:151], v[214:217], v[12:15]
	v_mfma_f32_16x16x32_bf16 v[8:11], v[156:159], v[214:217], v[8:11]
	s_setprio 0
	s_setprio 1
	v_mfma_f32_16x16x32_bf16 v[52:55], v[160:163], v[182:185], v[52:55]
	v_mfma_f32_16x16x32_bf16 v[48:51], v[168:171], v[182:185], v[48:51]
	v_mfma_f32_16x16x32_bf16 v[36:39], v[160:163], v[194:197], v[36:39]
	v_mfma_f32_16x16x32_bf16 v[32:35], v[168:171], v[194:197], v[32:35]
	v_mfma_f32_16x16x32_bf16 v[20:23], v[160:163], v[202:205], v[20:23]
	v_mfma_f32_16x16x32_bf16 v[16:19], v[168:171], v[202:205], v[16:19]
	v_mfma_f32_16x16x32_bf16 v[4:7], v[160:163], v[210:213], v[4:7]
	v_mfma_f32_16x16x32_bf16 v[0:3], v[168:171], v[210:213], v[0:3]
	v_mfma_f32_16x16x32_bf16 v[52:55], v[164:167], v[190:193], v[52:55]
	v_mfma_f32_16x16x32_bf16 v[48:51], v[178:181], v[190:193], v[48:51]
	v_mfma_f32_16x16x32_bf16 v[36:39], v[164:167], v[198:201], v[36:39]
	v_mfma_f32_16x16x32_bf16 v[32:35], v[178:181], v[198:201], v[32:35]
	v_mfma_f32_16x16x32_bf16 v[20:23], v[164:167], v[206:209], v[20:23]
	v_mfma_f32_16x16x32_bf16 v[16:19], v[178:181], v[206:209], v[16:19]
	v_mfma_f32_16x16x32_bf16 v[4:7], v[164:167], v[214:217], v[4:7]
	v_mfma_f32_16x16x32_bf16 v[0:3], v[178:181], v[214:217], v[0:3]
	s_setprio 0
	s_barrier
	s_add_i32 s62, 0, 0x18000
	s_add_i32 s64, 0, 0x1c000
	v_add_u32_e32 v156, s62, v173
	v_add_u32_e32 v178, s64, v173
	ds_read_b128 v[144:147], v156
	ds_read_b128 v[148:151], v156 offset:1024
	ds_read_b128 v[152:155], v156 offset:2048
	ds_read_b128 v[156:159], v156 offset:3072
	ds_read_b128 v[160:163], v178
	ds_read_b128 v[164:167], v178 offset:1024
	ds_read_b128 v[168:171], v178 offset:2048
	ds_read_b128 v[178:181], v178 offset:3072
	s_add_u32 s52, s52, 0x40000
	s_addc_u32 s53, s53, 0
	s_mov_b32 m0, s61
	v_lshl_add_u64 v[224:225], s[52:53], 0, v[128:129]
	ds_read_b128 v[182:185], v177 offset:32768
	ds_read_b128 v[190:193], v177 offset:33792
	ds_read_b128 v[194:197], v177 offset:34816
	ds_read_b128 v[198:201], v177 offset:35840
	ds_read_b128 v[202:205], v177 offset:36864
	ds_read_b128 v[206:209], v177 offset:37888
	ds_read_b128 v[210:213], v177 offset:38912
	ds_read_b128 v[214:217], v177 offset:39936
	global_load_lds_dwordx4 v[224:225], off
	v_lshl_add_u64 v[224:225], s[52:53], 0, v[132:133]
	s_mov_b32 m0, s66
	s_nop 0
	global_load_lds_dwordx4 v[224:225], off
	s_waitcnt vmcnt(8)
	s_waitcnt lgkmcnt(0)
	s_barrier
	s_setprio 1
	s_waitcnt lgkmcnt(0)
	v_mfma_f32_16x16x32_bf16 v[124:127], v[144:147], v[182:185], v[124:127]
	v_mfma_f32_16x16x32_bf16 v[120:123], v[152:155], v[182:185], v[120:123]
	v_mfma_f32_16x16x32_bf16 v[108:111], v[144:147], v[194:197], v[108:111]
	v_mfma_f32_16x16x32_bf16 v[104:107], v[152:155], v[194:197], v[104:107]
	v_mfma_f32_16x16x32_bf16 v[92:95], v[144:147], v[202:205], v[92:95]
	v_mfma_f32_16x16x32_bf16 v[88:91], v[152:155], v[202:205], v[88:91]
	v_mfma_f32_16x16x32_bf16 v[76:79], v[144:147], v[210:213], v[76:79]
	v_mfma_f32_16x16x32_bf16 v[72:75], v[152:155], v[210:213], v[72:75]
	v_mfma_f32_16x16x32_bf16 v[124:127], v[148:151], v[190:193], v[124:127]
	v_mfma_f32_16x16x32_bf16 v[120:123], v[156:159], v[190:193], v[120:123]
	v_mfma_f32_16x16x32_bf16 v[108:111], v[148:151], v[198:201], v[108:111]
	v_mfma_f32_16x16x32_bf16 v[104:107], v[156:159], v[198:201], v[104:107]
	v_mfma_f32_16x16x32_bf16 v[92:95], v[148:151], v[206:209], v[92:95]
	v_mfma_f32_16x16x32_bf16 v[88:91], v[156:159], v[206:209], v[88:91]
	v_mfma_f32_16x16x32_bf16 v[76:79], v[148:151], v[214:217], v[76:79]
	v_mfma_f32_16x16x32_bf16 v[72:75], v[156:159], v[214:217], v[72:75]
	s_setprio 0
	s_setprio 1
	v_mfma_f32_16x16x32_bf16 v[116:119], v[160:163], v[182:185], v[116:119]
	v_mfma_f32_16x16x32_bf16 v[112:115], v[168:171], v[182:185], v[112:115]
	v_mfma_f32_16x16x32_bf16 v[100:103], v[160:163], v[194:197], v[100:103]
	v_mfma_f32_16x16x32_bf16 v[96:99], v[168:171], v[194:197], v[96:99]
	v_mfma_f32_16x16x32_bf16 v[84:87], v[160:163], v[202:205], v[84:87]
	v_mfma_f32_16x16x32_bf16 v[80:83], v[168:171], v[202:205], v[80:83]
	v_mfma_f32_16x16x32_bf16 v[68:71], v[160:163], v[210:213], v[68:71]
	v_mfma_f32_16x16x32_bf16 v[64:67], v[168:171], v[210:213], v[64:67]
	v_mfma_f32_16x16x32_bf16 v[116:119], v[164:167], v[190:193], v[116:119]
	v_mfma_f32_16x16x32_bf16 v[112:115], v[178:181], v[190:193], v[112:115]
	v_mfma_f32_16x16x32_bf16 v[100:103], v[164:167], v[198:201], v[100:103]
	v_mfma_f32_16x16x32_bf16 v[96:99], v[178:181], v[198:201], v[96:99]
	v_mfma_f32_16x16x32_bf16 v[84:87], v[164:167], v[206:209], v[84:87]
	v_mfma_f32_16x16x32_bf16 v[80:83], v[178:181], v[206:209], v[80:83]
	v_mfma_f32_16x16x32_bf16 v[68:71], v[164:167], v[214:217], v[68:71]
	v_mfma_f32_16x16x32_bf16 v[64:67], v[178:181], v[214:217], v[64:67]
	s_setprio 0
	s_barrier
	s_add_i32 s52, s62, s58
	v_lshl_add_u64 v[186:187], v[186:187], 0, s[18:19]
	s_mov_b32 m0, s52
	ds_read_b128 v[182:185], v177 offset:49152
	ds_read_b128 v[190:193], v177 offset:50176
	ds_read_b128 v[194:197], v177 offset:51200
	ds_read_b128 v[198:201], v177 offset:52224
	ds_read_b128 v[202:205], v177 offset:53248
	ds_read_b128 v[206:209], v177 offset:54272
	ds_read_b128 v[210:213], v177 offset:55296
	ds_read_b128 v[214:217], v177 offset:56320
	global_load_lds_dwordx4 v[186:187], off
	s_add_i32 m0, s52, 0x2000
	s_add_u32 s50, s50, 0x40080
	v_lshl_add_u64 v[186:187], v[218:219], 0, s[18:19]
	s_addc_u32 s51, s51, 0
	s_add_i32 s52, s64, s58
	global_load_lds_dwordx4 v[186:187], off
	v_lshl_add_u64 v[186:187], s[50:51], 0, v[130:131]
	s_mov_b32 m0, s52
	s_nop 0
	global_load_lds_dwordx4 v[186:187], off
	v_lshl_add_u64 v[186:187], s[50:51], 0, v[134:135]
	s_add_i32 m0, s52, 0x2000
	s_nop 0
	global_load_lds_dwordx4 v[186:187], off
	v_lshl_add_u64 v[186:187], v[220:221], 0, s[18:19]
	s_mov_b32 m0, s68
	s_nop 0
	global_load_lds_dwordx4 v[186:187], off
	v_lshl_add_u64 v[186:187], v[222:223], 0, s[18:19]
	s_mov_b32 m0, s69
	s_nop 0
	global_load_lds_dwordx4 v[186:187], off
	s_waitcnt vmcnt(8)
	s_waitcnt lgkmcnt(0)
	s_barrier
	s_setprio 1
	s_waitcnt lgkmcnt(0)
	v_mfma_f32_16x16x32_bf16 v[60:63], v[144:147], v[182:185], v[60:63]
	v_mfma_f32_16x16x32_bf16 v[56:59], v[152:155], v[182:185], v[56:59]
	v_mfma_f32_16x16x32_bf16 v[44:47], v[144:147], v[194:197], v[44:47]
	v_mfma_f32_16x16x32_bf16 v[40:43], v[152:155], v[194:197], v[40:43]
	v_mfma_f32_16x16x32_bf16 v[28:31], v[144:147], v[202:205], v[28:31]
	v_mfma_f32_16x16x32_bf16 v[24:27], v[152:155], v[202:205], v[24:27]
	v_mfma_f32_16x16x32_bf16 v[12:15], v[144:147], v[210:213], v[12:15]
	v_mfma_f32_16x16x32_bf16 v[8:11], v[152:155], v[210:213], v[8:11]
	v_mfma_f32_16x16x32_bf16 v[60:63], v[148:151], v[190:193], v[60:63]
	v_mfma_f32_16x16x32_bf16 v[56:59], v[156:159], v[190:193], v[56:59]
	v_mfma_f32_16x16x32_bf16 v[44:47], v[148:151], v[198:201], v[44:47]
	v_mfma_f32_16x16x32_bf16 v[40:43], v[156:159], v[198:201], v[40:43]
	v_mfma_f32_16x16x32_bf16 v[28:31], v[148:151], v[206:209], v[28:31]
	v_mfma_f32_16x16x32_bf16 v[24:27], v[156:159], v[206:209], v[24:27]
	v_mfma_f32_16x16x32_bf16 v[12:15], v[148:151], v[214:217], v[12:15]
	v_mfma_f32_16x16x32_bf16 v[8:11], v[156:159], v[214:217], v[8:11]
	s_setprio 0
	s_setprio 1
	v_mfma_f32_16x16x32_bf16 v[52:55], v[160:163], v[182:185], v[52:55]
	v_mfma_f32_16x16x32_bf16 v[48:51], v[168:171], v[182:185], v[48:51]
	v_mfma_f32_16x16x32_bf16 v[36:39], v[160:163], v[194:197], v[36:39]
	v_mfma_f32_16x16x32_bf16 v[32:35], v[168:171], v[194:197], v[32:35]
	v_mfma_f32_16x16x32_bf16 v[20:23], v[160:163], v[202:205], v[20:23]
	v_mfma_f32_16x16x32_bf16 v[16:19], v[168:171], v[202:205], v[16:19]
	v_mfma_f32_16x16x32_bf16 v[4:7], v[160:163], v[210:213], v[4:7]
	v_mfma_f32_16x16x32_bf16 v[0:3], v[168:171], v[210:213], v[0:3]
	v_mfma_f32_16x16x32_bf16 v[52:55], v[164:167], v[190:193], v[52:55]
	v_mfma_f32_16x16x32_bf16 v[48:51], v[178:181], v[190:193], v[48:51]
	v_mfma_f32_16x16x32_bf16 v[36:39], v[164:167], v[198:201], v[36:39]
	v_mfma_f32_16x16x32_bf16 v[32:35], v[178:181], v[198:201], v[32:35]
	v_mfma_f32_16x16x32_bf16 v[20:23], v[164:167], v[206:209], v[20:23]
	v_mfma_f32_16x16x32_bf16 v[16:19], v[178:181], v[206:209], v[16:19]
	v_mfma_f32_16x16x32_bf16 v[4:7], v[164:167], v[214:217], v[4:7]
	v_mfma_f32_16x16x32_bf16 v[0:3], v[178:181], v[214:217], v[0:3]
	s_add_i32 s78, s78, 2
	s_add_u32 s48, s48, 0x100
	s_addc_u32 s49, s49, 0
	s_add_u32 s63, s63, 0x100
	s_addc_u32 s77, s77, 0
	s_cmp_gt_u32 s78, 13
	s_setprio 0
	s_barrier
	s_cbranch_scc0 .LBB0_881
	s_and_b64 vcc, exec, s[34:35]
	s_cbranch_vccz .LBB0_884
	s_barrier

.LBB0_1144:
	ds_read_b128 v[150:153], v147
	ds_read_b128 v[154:157], v147 offset:1024
	ds_read_b128 v[158:161], v147 offset:2048
	ds_read_b128 v[162:165], v147 offset:3072
	ds_read_b128 v[166:169], v148
	ds_read_b128 v[170:173], v148 offset:1024
	ds_read_b128 v[174:177], v148 offset:2048
	ds_read_b128 v[178:181], v148 offset:3072
	s_add_u32 s44, s42, 0xfffc0080
	s_addc_u32 s45, s43, -1
	s_cmp_eq_u32 s75, 12
	s_cselect_b32 s47, s31, s45
	s_cselect_b32 s46, s71, s44
	s_cselect_b32 s45, s35, s74
	s_cselect_b32 s44, s72, s73
	v_lshl_add_u64 v[186:187], s[42:43], 0, v[136:137]
	s_add_i32 m0, s37, 0xc000
	ds_read_b128 v[182:185], v149
	ds_read_b128 v[190:193], v149 offset:1024
	ds_read_b128 v[194:197], v149 offset:2048
	ds_read_b128 v[198:201], v149 offset:3072
	ds_read_b128 v[202:205], v149 offset:4096
	ds_read_b128 v[206:209], v149 offset:5120
	ds_read_b128 v[210:213], v149 offset:6144
	ds_read_b128 v[214:217], v149 offset:7168
	global_load_lds_dwordx4 v[186:187], off
	v_lshl_add_u64 v[186:187], s[42:43], 0, v[138:139]
	s_add_i32 m0, s37, 0xe000
	s_nop 0
	global_load_lds_dwordx4 v[186:187], off
	s_waitcnt vmcnt(8)
	s_waitcnt lgkmcnt(0)
	s_barrier
	s_setprio 1
	s_waitcnt lgkmcnt(0)
	v_mfma_f32_16x16x32_bf16 v[124:127], v[150:153], v[182:185], v[124:127]
	v_mfma_f32_16x16x32_bf16 v[120:123], v[158:161], v[182:185], v[120:123]
	v_mfma_f32_16x16x32_bf16 v[116:119], v[150:153], v[194:197], v[116:119]
	v_mfma_f32_16x16x32_bf16 v[112:115], v[158:161], v[194:197], v[112:115]
	v_mfma_f32_16x16x32_bf16 v[100:103], v[150:153], v[202:205], v[100:103]
	v_mfma_f32_16x16x32_bf16 v[96:99], v[158:161], v[202:205], v[96:99]
	v_mfma_f32_16x16x32_bf16 v[84:87], v[150:153], v[210:213], v[84:87]
	v_mfma_f32_16x16x32_bf16 v[80:83], v[158:161], v[210:213], v[80:83]
	v_mfma_f32_16x16x32_bf16 v[124:127], v[154:157], v[190:193], v[124:127]
	v_mfma_f32_16x16x32_bf16 v[120:123], v[162:165], v[190:193], v[120:123]
	v_mfma_f32_16x16x32_bf16 v[116:119], v[154:157], v[198:201], v[116:119]
	v_mfma_f32_16x16x32_bf16 v[112:115], v[162:165], v[198:201], v[112:115]
	v_mfma_f32_16x16x32_bf16 v[100:103], v[154:157], v[206:209], v[100:103]
	v_mfma_f32_16x16x32_bf16 v[96:99], v[162:165], v[206:209], v[96:99]
	v_mfma_f32_16x16x32_bf16 v[84:87], v[154:157], v[214:217], v[84:87]
	v_mfma_f32_16x16x32_bf16 v[80:83], v[162:165], v[214:217], v[80:83]
	s_setprio 0
	s_setprio 1
	v_mfma_f32_16x16x32_bf16 v[108:111], v[166:169], v[182:185], v[108:111]
	v_mfma_f32_16x16x32_bf16 v[104:107], v[174:177], v[182:185], v[104:107]
	v_mfma_f32_16x16x32_bf16 v[92:95], v[166:169], v[194:197], v[92:95]
	v_mfma_f32_16x16x32_bf16 v[88:91], v[174:177], v[194:197], v[88:91]
	v_mfma_f32_16x16x32_bf16 v[76:79], v[166:169], v[202:205], v[76:79]
	v_mfma_f32_16x16x32_bf16 v[72:75], v[174:177], v[202:205], v[72:75]
	v_mfma_f32_16x16x32_bf16 v[68:71], v[166:169], v[210:213], v[68:71]
	v_mfma_f32_16x16x32_bf16 v[64:67], v[174:177], v[210:213], v[64:67]
	v_mfma_f32_16x16x32_bf16 v[108:111], v[170:173], v[190:193], v[108:111]
	v_mfma_f32_16x16x32_bf16 v[104:107], v[178:181], v[190:193], v[104:107]
	v_mfma_f32_16x16x32_bf16 v[92:95], v[170:173], v[198:201], v[92:95]
	v_mfma_f32_16x16x32_bf16 v[88:91], v[178:181], v[198:201], v[88:91]
	v_mfma_f32_16x16x32_bf16 v[76:79], v[170:173], v[206:209], v[76:79]
	v_mfma_f32_16x16x32_bf16 v[72:75], v[178:181], v[206:209], v[72:75]
	v_mfma_f32_16x16x32_bf16 v[68:71], v[170:173], v[214:217], v[68:71]
	v_mfma_f32_16x16x32_bf16 v[64:67], v[178:181], v[214:217], v[64:67]
	s_setprio 0
	s_barrier
	s_add_i32 s62, s63, s52
	v_lshl_add_u64 v[186:187], s[44:45], 0, v[132:133]
	s_mov_b32 m0, s62
	ds_read_b128 v[182:185], v149 offset:16384
	ds_read_b128 v[190:193], v149 offset:17408
	ds_read_b128 v[194:197], v149 offset:18432
	ds_read_b128 v[198:201], v149 offset:19456
	ds_read_b128 v[202:205], v149 offset:20480
	ds_read_b128 v[206:209], v149 offset:21504
	ds_read_b128 v[210:213], v149 offset:22528
	ds_read_b128 v[214:217], v149 offset:23552
	global_load_lds_dwordx4 v[186:187], off
	s_add_i32 m0, s62, 0x2000
	s_add_u32 s76, s44, 0x40000
	v_lshl_add_u64 v[218:219], s[44:45], 0, v[128:129]
	s_addc_u32 s77, s45, 0
	s_add_i32 s62, s65, s52
	global_load_lds_dwordx4 v[218:219], off
	v_lshl_add_u64 v[220:221], s[76:77], 0, v[132:133]
	s_mov_b32 m0, s62
	v_lshl_add_u64 v[222:223], s[46:47], 0, v[130:131]
	global_load_lds_dwordx4 v[220:221], off
	v_lshl_add_u64 v[220:221], s[76:77], 0, v[128:129]
	s_add_i32 m0, s62, 0x2000
	s_nop 0
	global_load_lds_dwordx4 v[220:221], off
	v_lshl_add_u64 v[220:221], s[46:47], 0, v[134:135]
	s_mov_b32 m0, s37
	s_nop 0
	global_load_lds_dwordx4 v[220:221], off
	s_mov_b32 m0, s54
	s_nop 0
	global_load_lds_dwordx4 v[222:223], off
	s_waitcnt vmcnt(8)
	s_waitcnt lgkmcnt(0)
	s_barrier
	s_setprio 1
	s_waitcnt lgkmcnt(0)
	v_mfma_f32_16x16x32_bf16 v[60:63], v[150:153], v[182:185], v[60:63]
	v_mfma_f32_16x16x32_bf16 v[56:59], v[158:161], v[182:185], v[56:59]
	v_mfma_f32_16x16x32_bf16 v[52:55], v[150:153], v[194:197], v[52:55]
	v_mfma_f32_16x16x32_bf16 v[48:51], v[158:161], v[194:197], v[48:51]
	v_mfma_f32_16x16x32_bf16 v[36:39], v[150:153], v[202:205], v[36:39]
	v_mfma_f32_16x16x32_bf16 v[32:35], v[158:161], v[202:205], v[32:35]
	v_mfma_f32_16x16x32_bf16 v[20:23], v[150:153], v[210:213], v[20:23]
	v_mfma_f32_16x16x32_bf16 v[16:19], v[158:161], v[210:213], v[16:19]
	v_mfma_f32_16x16x32_bf16 v[60:63], v[154:157], v[190:193], v[60:63]
	v_mfma_f32_16x16x32_bf16 v[56:59], v[162:165], v[190:193], v[56:59]
	v_mfma_f32_16x16x32_bf16 v[52:55], v[154:157], v[198:201], v[52:55]
	v_mfma_f32_16x16x32_bf16 v[48:51], v[162:165], v[198:201], v[48:51]
	v_mfma_f32_16x16x32_bf16 v[36:39], v[154:157], v[206:209], v[36:39]
	v_mfma_f32_16x16x32_bf16 v[32:35], v[162:165], v[206:209], v[32:35]
	v_mfma_f32_16x16x32_bf16 v[20:23], v[154:157], v[214:217], v[20:23]
	v_mfma_f32_16x16x32_bf16 v[16:19], v[162:165], v[214:217], v[16:19]
	s_setprio 0
	s_setprio 1
	v_mfma_f32_16x16x32_bf16 v[44:47], v[166:169], v[182:185], v[44:47]
	v_mfma_f32_16x16x32_bf16 v[40:43], v[174:177], v[182:185], v[40:43]
	v_mfma_f32_16x16x32_bf16 v[28:31], v[166:169], v[194:197], v[28:31]
	v_mfma_f32_16x16x32_bf16 v[24:27], v[174:177], v[194:197], v[24:27]
	v_mfma_f32_16x16x32_bf16 v[12:15], v[166:169], v[202:205], v[12:15]
	v_mfma_f32_16x16x32_bf16 v[8:11], v[174:177], v[202:205], v[8:11]
	v_mfma_f32_16x16x32_bf16 v[4:7], v[166:169], v[210:213], v[4:7]
	v_mfma_f32_16x16x32_bf16 v[0:3], v[174:177], v[210:213], v[0:3]
	v_mfma_f32_16x16x32_bf16 v[44:47], v[170:173], v[190:193], v[44:47]
	v_mfma_f32_16x16x32_bf16 v[40:43], v[178:181], v[190:193], v[40:43]
	v_mfma_f32_16x16x32_bf16 v[28:31], v[170:173], v[198:201], v[28:31]
	v_mfma_f32_16x16x32_bf16 v[24:27], v[178:181], v[198:201], v[24:27]
	v_mfma_f32_16x16x32_bf16 v[12:15], v[170:173], v[206:209], v[12:15]
	v_mfma_f32_16x16x32_bf16 v[8:11], v[178:181], v[206:209], v[8:11]
	v_mfma_f32_16x16x32_bf16 v[4:7], v[170:173], v[214:217], v[4:7]
	v_mfma_f32_16x16x32_bf16 v[0:3], v[178:181], v[214:217], v[0:3]
	s_setprio 0
	s_barrier
	s_add_i32 s62, 0, 0x18000
	s_add_i32 s64, 0, 0x1c000
	v_add_u32_e32 v162, s62, v145
	v_add_u32_e32 v178, s64, v145
	ds_read_b128 v[150:153], v162
	ds_read_b128 v[154:157], v162 offset:1024
	ds_read_b128 v[158:161], v162 offset:2048
	ds_read_b128 v[162:165], v162 offset:3072
	ds_read_b128 v[166:169], v178
	ds_read_b128 v[170:173], v178 offset:1024
	ds_read_b128 v[174:177], v178 offset:2048
	ds_read_b128 v[178:181], v178 offset:3072
	s_add_u32 s46, s46, 0x40000
	s_addc_u32 s47, s47, 0
	s_mov_b32 m0, s55
	v_lshl_add_u64 v[224:225], s[46:47], 0, v[134:135]
	ds_read_b128 v[182:185], v149 offset:32768
	ds_read_b128 v[190:193], v149 offset:33792
	ds_read_b128 v[194:197], v149 offset:34816
	ds_read_b128 v[198:201], v149 offset:35840
	ds_read_b128 v[202:205], v149 offset:36864
	ds_read_b128 v[206:209], v149 offset:37888
	ds_read_b128 v[210:213], v149 offset:38912
	ds_read_b128 v[214:217], v149 offset:39936
	global_load_lds_dwordx4 v[224:225], off
	v_lshl_add_u64 v[224:225], s[46:47], 0, v[130:131]
	s_mov_b32 m0, s56
	s_nop 0
	global_load_lds_dwordx4 v[224:225], off
	s_waitcnt vmcnt(8)
	s_waitcnt lgkmcnt(0)
	s_barrier
	s_setprio 1
	s_waitcnt lgkmcnt(0)
	v_mfma_f32_16x16x32_bf16 v[124:127], v[150:153], v[182:185], v[124:127]
	v_mfma_f32_16x16x32_bf16 v[120:123], v[158:161], v[182:185], v[120:123]
	v_mfma_f32_16x16x32_bf16 v[116:119], v[150:153], v[194:197], v[116:119]
	v_mfma_f32_16x16x32_bf16 v[112:115], v[158:161], v[194:197], v[112:115]
	v_mfma_f32_16x16x32_bf16 v[100:103], v[150:153], v[202:205], v[100:103]
	v_mfma_f32_16x16x32_bf16 v[96:99], v[158:161], v[202:205], v[96:99]
	v_mfma_f32_16x16x32_bf16 v[84:87], v[150:153], v[210:213], v[84:87]
	v_mfma_f32_16x16x32_bf16 v[80:83], v[158:161], v[210:213], v[80:83]
	v_mfma_f32_16x16x32_bf16 v[124:127], v[154:157], v[190:193], v[124:127]
	v_mfma_f32_16x16x32_bf16 v[120:123], v[162:165], v[190:193], v[120:123]
	v_mfma_f32_16x16x32_bf16 v[116:119], v[154:157], v[198:201], v[116:119]
	v_mfma_f32_16x16x32_bf16 v[112:115], v[162:165], v[198:201], v[112:115]
	v_mfma_f32_16x16x32_bf16 v[100:103], v[154:157], v[206:209], v[100:103]
	v_mfma_f32_16x16x32_bf16 v[96:99], v[162:165], v[206:209], v[96:99]
	v_mfma_f32_16x16x32_bf16 v[84:87], v[154:157], v[214:217], v[84:87]
	v_mfma_f32_16x16x32_bf16 v[80:83], v[162:165], v[214:217], v[80:83]
	s_setprio 0
	s_setprio 1
	v_mfma_f32_16x16x32_bf16 v[108:111], v[166:169], v[182:185], v[108:111]
	v_mfma_f32_16x16x32_bf16 v[104:107], v[174:177], v[182:185], v[104:107]
	v_mfma_f32_16x16x32_bf16 v[92:95], v[166:169], v[194:197], v[92:95]
	v_mfma_f32_16x16x32_bf16 v[88:91], v[174:177], v[194:197], v[88:91]
	v_mfma_f32_16x16x32_bf16 v[76:79], v[166:169], v[202:205], v[76:79]
	v_mfma_f32_16x16x32_bf16 v[72:75], v[174:177], v[202:205], v[72:75]
	v_mfma_f32_16x16x32_bf16 v[68:71], v[166:169], v[210:213], v[68:71]
	v_mfma_f32_16x16x32_bf16 v[64:67], v[174:177], v[210:213], v[64:67]
	v_mfma_f32_16x16x32_bf16 v[108:111], v[170:173], v[190:193], v[108:111]
	v_mfma_f32_16x16x32_bf16 v[104:107], v[178:181], v[190:193], v[104:107]
	v_mfma_f32_16x16x32_bf16 v[92:95], v[170:173], v[198:201], v[92:95]
	v_mfma_f32_16x16x32_bf16 v[88:91], v[178:181], v[198:201], v[88:91]
	v_mfma_f32_16x16x32_bf16 v[76:79], v[170:173], v[206:209], v[76:79]
	v_mfma_f32_16x16x32_bf16 v[72:75], v[178:181], v[206:209], v[72:75]
	v_mfma_f32_16x16x32_bf16 v[68:71], v[170:173], v[214:217], v[68:71]
	v_mfma_f32_16x16x32_bf16 v[64:67], v[178:181], v[214:217], v[64:67]
	s_setprio 0
	s_barrier
	s_add_i32 s46, s62, s52
	v_lshl_add_u64 v[186:187], v[186:187], 0, s[10:11]
	s_mov_b32 m0, s46
	ds_read_b128 v[182:185], v149 offset:49152
	ds_read_b128 v[190:193], v149 offset:50176
	ds_read_b128 v[194:197], v149 offset:51200
	ds_read_b128 v[198:201], v149 offset:52224
	ds_read_b128 v[202:205], v149 offset:53248
	ds_read_b128 v[206:209], v149 offset:54272
	ds_read_b128 v[210:213], v149 offset:55296
	ds_read_b128 v[214:217], v149 offset:56320
	global_load_lds_dwordx4 v[186:187], off
	s_add_i32 m0, s46, 0x2000
	s_add_u32 s44, s44, 0x40080
	v_lshl_add_u64 v[186:187], v[218:219], 0, s[10:11]
	s_addc_u32 s45, s45, 0
	s_add_i32 s46, s64, s52
	global_load_lds_dwordx4 v[186:187], off
	v_lshl_add_u64 v[186:187], s[44:45], 0, v[132:133]
	s_mov_b32 m0, s46
	s_nop 0
	global_load_lds_dwordx4 v[186:187], off
	v_lshl_add_u64 v[186:187], s[44:45], 0, v[128:129]
	s_add_i32 m0, s46, 0x2000
	s_nop 0
	global_load_lds_dwordx4 v[186:187], off
	v_lshl_add_u64 v[186:187], v[220:221], 0, s[10:11]
	s_mov_b32 m0, s57
	s_nop 0
	global_load_lds_dwordx4 v[186:187], off
	v_lshl_add_u64 v[186:187], v[222:223], 0, s[10:11]
	s_mov_b32 m0, s58
	s_nop 0
	global_load_lds_dwordx4 v[186:187], off
	s_waitcnt vmcnt(8)
	s_waitcnt lgkmcnt(0)
	s_barrier
	s_setprio 1
	s_waitcnt lgkmcnt(0)
	v_mfma_f32_16x16x32_bf16 v[60:63], v[150:153], v[182:185], v[60:63]
	v_mfma_f32_16x16x32_bf16 v[56:59], v[158:161], v[182:185], v[56:59]
	v_mfma_f32_16x16x32_bf16 v[52:55], v[150:153], v[194:197], v[52:55]
	v_mfma_f32_16x16x32_bf16 v[48:51], v[158:161], v[194:197], v[48:51]
	v_mfma_f32_16x16x32_bf16 v[36:39], v[150:153], v[202:205], v[36:39]
	v_mfma_f32_16x16x32_bf16 v[32:35], v[158:161], v[202:205], v[32:35]
	v_mfma_f32_16x16x32_bf16 v[20:23], v[150:153], v[210:213], v[20:23]
	v_mfma_f32_16x16x32_bf16 v[16:19], v[158:161], v[210:213], v[16:19]
	v_mfma_f32_16x16x32_bf16 v[60:63], v[154:157], v[190:193], v[60:63]
	v_mfma_f32_16x16x32_bf16 v[56:59], v[162:165], v[190:193], v[56:59]
	v_mfma_f32_16x16x32_bf16 v[52:55], v[154:157], v[198:201], v[52:55]
	v_mfma_f32_16x16x32_bf16 v[48:51], v[162:165], v[198:201], v[48:51]
	v_mfma_f32_16x16x32_bf16 v[36:39], v[154:157], v[206:209], v[36:39]
	v_mfma_f32_16x16x32_bf16 v[32:35], v[162:165], v[206:209], v[32:35]
	v_mfma_f32_16x16x32_bf16 v[20:23], v[154:157], v[214:217], v[20:23]
	v_mfma_f32_16x16x32_bf16 v[16:19], v[162:165], v[214:217], v[16:19]
	s_setprio 0
	s_setprio 1
	v_mfma_f32_16x16x32_bf16 v[44:47], v[166:169], v[182:185], v[44:47]
	v_mfma_f32_16x16x32_bf16 v[40:43], v[174:177], v[182:185], v[40:43]
	v_mfma_f32_16x16x32_bf16 v[28:31], v[166:169], v[194:197], v[28:31]
	v_mfma_f32_16x16x32_bf16 v[24:27], v[174:177], v[194:197], v[24:27]
	v_mfma_f32_16x16x32_bf16 v[12:15], v[166:169], v[202:205], v[12:15]
	v_mfma_f32_16x16x32_bf16 v[8:11], v[174:177], v[202:205], v[8:11]
	v_mfma_f32_16x16x32_bf16 v[4:7], v[166:169], v[210:213], v[4:7]
	v_mfma_f32_16x16x32_bf16 v[0:3], v[174:177], v[210:213], v[0:3]
	v_mfma_f32_16x16x32_bf16 v[44:47], v[170:173], v[190:193], v[44:47]
	v_mfma_f32_16x16x32_bf16 v[40:43], v[178:181], v[190:193], v[40:43]
	v_mfma_f32_16x16x32_bf16 v[28:31], v[170:173], v[198:201], v[28:31]
	v_mfma_f32_16x16x32_bf16 v[24:27], v[178:181], v[198:201], v[24:27]
	v_mfma_f32_16x16x32_bf16 v[12:15], v[170:173], v[206:209], v[12:15]
	v_mfma_f32_16x16x32_bf16 v[8:11], v[178:181], v[206:209], v[8:11]
	v_mfma_f32_16x16x32_bf16 v[4:7], v[170:173], v[214:217], v[4:7]
	v_mfma_f32_16x16x32_bf16 v[0:3], v[178:181], v[214:217], v[0:3]
	s_add_i32 s75, s75, 2
	s_add_u32 s42, s42, 0x100
	s_addc_u32 s43, s43, 0
	s_add_u32 s73, s73, 0x100
	s_addc_u32 s74, s74, 0
	s_cmp_gt_u32 s75, 13
	s_setprio 0
	s_barrier
	s_cbranch_scc0 .LBB0_1144
	s_and_b64 vcc, exec, s[12:13]
	s_cbranch_vccz .LBB0_1147
	s_barrier

.LBB0_1303:
	ds_read_b128 v[152:155], v149
	ds_read_b128 v[156:159], v149 offset:1024
	ds_read_b128 v[160:163], v149 offset:2048
	ds_read_b128 v[164:167], v149 offset:3072
	ds_read_b128 v[168:171], v150
	ds_read_b128 v[172:175], v150 offset:1024
	ds_read_b128 v[176:179], v150 offset:2048
	ds_read_b128 v[180:183], v150 offset:3072
	s_add_u32 s42, s40, 0xfffc0080
	s_addc_u32 s43, s41, -1
	s_cmp_eq_u32 s75, 12
	s_cselect_b32 s45, s31, s43
	s_cselect_b32 s44, s71, s42
	s_cselect_b32 s43, s29, s74
	s_cselect_b32 s42, s72, s73
	v_lshl_add_u64 v[144:145], s[40:41], 0, v[136:137]
	s_add_i32 m0, s39, 0xc000
	ds_read_b128 v[184:187], v151
	ds_read_b128 v[190:193], v151 offset:1024
	ds_read_b128 v[194:197], v151 offset:2048
	ds_read_b128 v[198:201], v151 offset:3072
	ds_read_b128 v[202:205], v151 offset:4096
	ds_read_b128 v[206:209], v151 offset:5120
	ds_read_b128 v[210:213], v151 offset:6144
	ds_read_b128 v[214:217], v151 offset:7168
	global_load_lds_dwordx4 v[144:145], off
	v_lshl_add_u64 v[144:145], s[40:41], 0, v[138:139]
	s_add_i32 m0, s39, 0xe000
	s_nop 0
	global_load_lds_dwordx4 v[144:145], off
	s_waitcnt vmcnt(8)
	s_waitcnt lgkmcnt(0)
	s_barrier
	s_setprio 1
	s_waitcnt lgkmcnt(0)
	v_mfma_f32_16x16x32_bf16 v[124:127], v[152:155], v[184:187], v[124:127]
	v_mfma_f32_16x16x32_bf16 v[120:123], v[160:163], v[184:187], v[120:123]
	v_mfma_f32_16x16x32_bf16 v[108:111], v[152:155], v[194:197], v[108:111]
	v_mfma_f32_16x16x32_bf16 v[104:107], v[160:163], v[194:197], v[104:107]
	v_mfma_f32_16x16x32_bf16 v[92:95], v[152:155], v[202:205], v[92:95]
	v_mfma_f32_16x16x32_bf16 v[88:91], v[160:163], v[202:205], v[88:91]
	v_mfma_f32_16x16x32_bf16 v[76:79], v[152:155], v[210:213], v[76:79]
	v_mfma_f32_16x16x32_bf16 v[72:75], v[160:163], v[210:213], v[72:75]
	v_mfma_f32_16x16x32_bf16 v[124:127], v[156:159], v[190:193], v[124:127]
	v_mfma_f32_16x16x32_bf16 v[120:123], v[164:167], v[190:193], v[120:123]
	v_mfma_f32_16x16x32_bf16 v[108:111], v[156:159], v[198:201], v[108:111]
	v_mfma_f32_16x16x32_bf16 v[104:107], v[164:167], v[198:201], v[104:107]
	v_mfma_f32_16x16x32_bf16 v[92:95], v[156:159], v[206:209], v[92:95]
	v_mfma_f32_16x16x32_bf16 v[88:91], v[164:167], v[206:209], v[88:91]
	v_mfma_f32_16x16x32_bf16 v[76:79], v[156:159], v[214:217], v[76:79]
	v_mfma_f32_16x16x32_bf16 v[72:75], v[164:167], v[214:217], v[72:75]
	s_setprio 0
	s_setprio 1
	v_mfma_f32_16x16x32_bf16 v[116:119], v[168:171], v[184:187], v[116:119]
	v_mfma_f32_16x16x32_bf16 v[112:115], v[176:179], v[184:187], v[112:115]
	v_mfma_f32_16x16x32_bf16 v[100:103], v[168:171], v[194:197], v[100:103]
	v_mfma_f32_16x16x32_bf16 v[96:99], v[176:179], v[194:197], v[96:99]
	v_mfma_f32_16x16x32_bf16 v[84:87], v[168:171], v[202:205], v[84:87]
	v_mfma_f32_16x16x32_bf16 v[80:83], v[176:179], v[202:205], v[80:83]
	v_mfma_f32_16x16x32_bf16 v[68:71], v[168:171], v[210:213], v[68:71]
	v_mfma_f32_16x16x32_bf16 v[64:67], v[176:179], v[210:213], v[64:67]
	v_mfma_f32_16x16x32_bf16 v[116:119], v[172:175], v[190:193], v[116:119]
	v_mfma_f32_16x16x32_bf16 v[112:115], v[180:183], v[190:193], v[112:115]
	v_mfma_f32_16x16x32_bf16 v[100:103], v[172:175], v[198:201], v[100:103]
	v_mfma_f32_16x16x32_bf16 v[96:99], v[180:183], v[198:201], v[96:99]
	v_mfma_f32_16x16x32_bf16 v[84:87], v[172:175], v[206:209], v[84:87]
	v_mfma_f32_16x16x32_bf16 v[80:83], v[180:183], v[206:209], v[80:83]
	v_mfma_f32_16x16x32_bf16 v[68:71], v[172:175], v[214:217], v[68:71]
	v_mfma_f32_16x16x32_bf16 v[64:67], v[180:183], v[214:217], v[64:67]
	s_setprio 0
	s_barrier
	s_add_i32 s62, s63, s51
	v_lshl_add_u64 v[144:145], s[42:43], 0, v[132:133]
	s_mov_b32 m0, s62
	ds_read_b128 v[184:187], v151 offset:16384
	ds_read_b128 v[190:193], v151 offset:17408
	ds_read_b128 v[194:197], v151 offset:18432
	ds_read_b128 v[198:201], v151 offset:19456
	ds_read_b128 v[202:205], v151 offset:20480
	ds_read_b128 v[206:209], v151 offset:21504
	ds_read_b128 v[210:213], v151 offset:22528
	ds_read_b128 v[214:217], v151 offset:23552
	global_load_lds_dwordx4 v[144:145], off
	s_add_i32 m0, s62, 0x2000
	s_add_u32 s76, s42, 0x40000
	v_lshl_add_u64 v[218:219], s[42:43], 0, v[128:129]
	s_addc_u32 s77, s43, 0
	s_add_i32 s62, s65, s51
	global_load_lds_dwordx4 v[218:219], off
	v_lshl_add_u64 v[220:221], s[76:77], 0, v[132:133]
	s_mov_b32 m0, s62
	v_lshl_add_u64 v[222:223], s[44:45], 0, v[130:131]
	global_load_lds_dwordx4 v[220:221], off
	v_lshl_add_u64 v[220:221], s[76:77], 0, v[128:129]
	s_add_i32 m0, s62, 0x2000
	s_nop 0
	global_load_lds_dwordx4 v[220:221], off
	v_lshl_add_u64 v[220:221], s[44:45], 0, v[134:135]
	s_mov_b32 m0, s39
	s_nop 0
	global_load_lds_dwordx4 v[220:221], off
	s_mov_b32 m0, s54
	s_nop 0
	global_load_lds_dwordx4 v[222:223], off
	s_waitcnt vmcnt(8)
	s_waitcnt lgkmcnt(0)
	s_barrier
	s_setprio 1
	s_waitcnt lgkmcnt(0)
	v_mfma_f32_16x16x32_bf16 v[60:63], v[152:155], v[184:187], v[60:63]
	v_mfma_f32_16x16x32_bf16 v[56:59], v[160:163], v[184:187], v[56:59]
	v_mfma_f32_16x16x32_bf16 v[44:47], v[152:155], v[194:197], v[44:47]
	v_mfma_f32_16x16x32_bf16 v[40:43], v[160:163], v[194:197], v[40:43]
	v_mfma_f32_16x16x32_bf16 v[28:31], v[152:155], v[202:205], v[28:31]
	v_mfma_f32_16x16x32_bf16 v[24:27], v[160:163], v[202:205], v[24:27]
	v_mfma_f32_16x16x32_bf16 v[12:15], v[152:155], v[210:213], v[12:15]
	v_mfma_f32_16x16x32_bf16 v[8:11], v[160:163], v[210:213], v[8:11]
	v_mfma_f32_16x16x32_bf16 v[60:63], v[156:159], v[190:193], v[60:63]
	v_mfma_f32_16x16x32_bf16 v[56:59], v[164:167], v[190:193], v[56:59]
	v_mfma_f32_16x16x32_bf16 v[44:47], v[156:159], v[198:201], v[44:47]
	v_mfma_f32_16x16x32_bf16 v[40:43], v[164:167], v[198:201], v[40:43]
	v_mfma_f32_16x16x32_bf16 v[28:31], v[156:159], v[206:209], v[28:31]
	v_mfma_f32_16x16x32_bf16 v[24:27], v[164:167], v[206:209], v[24:27]
	v_mfma_f32_16x16x32_bf16 v[12:15], v[156:159], v[214:217], v[12:15]
	v_mfma_f32_16x16x32_bf16 v[8:11], v[164:167], v[214:217], v[8:11]
	s_setprio 0
	s_setprio 1
	v_mfma_f32_16x16x32_bf16 v[52:55], v[168:171], v[184:187], v[52:55]
	v_mfma_f32_16x16x32_bf16 v[48:51], v[176:179], v[184:187], v[48:51]
	v_mfma_f32_16x16x32_bf16 v[36:39], v[168:171], v[194:197], v[36:39]
	v_mfma_f32_16x16x32_bf16 v[32:35], v[176:179], v[194:197], v[32:35]
	v_mfma_f32_16x16x32_bf16 v[20:23], v[168:171], v[202:205], v[20:23]
	v_mfma_f32_16x16x32_bf16 v[16:19], v[176:179], v[202:205], v[16:19]
	v_mfma_f32_16x16x32_bf16 v[4:7], v[168:171], v[210:213], v[4:7]
	v_mfma_f32_16x16x32_bf16 v[0:3], v[176:179], v[210:213], v[0:3]
	v_mfma_f32_16x16x32_bf16 v[52:55], v[172:175], v[190:193], v[52:55]
	v_mfma_f32_16x16x32_bf16 v[48:51], v[180:183], v[190:193], v[48:51]
	v_mfma_f32_16x16x32_bf16 v[36:39], v[172:175], v[198:201], v[36:39]
	v_mfma_f32_16x16x32_bf16 v[32:35], v[180:183], v[198:201], v[32:35]
	v_mfma_f32_16x16x32_bf16 v[20:23], v[172:175], v[206:209], v[20:23]
	v_mfma_f32_16x16x32_bf16 v[16:19], v[180:183], v[206:209], v[16:19]
	v_mfma_f32_16x16x32_bf16 v[4:7], v[172:175], v[214:217], v[4:7]
	v_mfma_f32_16x16x32_bf16 v[0:3], v[180:183], v[214:217], v[0:3]
	s_setprio 0
	s_barrier
	s_add_i32 s62, 0, 0x18000
	s_add_i32 s64, 0, 0x1c000
	v_add_u32_e32 v164, s62, v147
	v_add_u32_e32 v180, s64, v147
	ds_read_b128 v[152:155], v164
	ds_read_b128 v[156:159], v164 offset:1024
	ds_read_b128 v[160:163], v164 offset:2048
	ds_read_b128 v[164:167], v164 offset:3072
	ds_read_b128 v[168:171], v180
	ds_read_b128 v[172:175], v180 offset:1024
	ds_read_b128 v[176:179], v180 offset:2048
	ds_read_b128 v[180:183], v180 offset:3072
	s_add_u32 s44, s44, 0x40000
	s_addc_u32 s45, s45, 0
	s_mov_b32 m0, s55
	v_lshl_add_u64 v[224:225], s[44:45], 0, v[134:135]
	ds_read_b128 v[184:187], v151 offset:32768
	ds_read_b128 v[190:193], v151 offset:33792
	ds_read_b128 v[194:197], v151 offset:34816
	ds_read_b128 v[198:201], v151 offset:35840
	ds_read_b128 v[202:205], v151 offset:36864
	ds_read_b128 v[206:209], v151 offset:37888
	ds_read_b128 v[210:213], v151 offset:38912
	ds_read_b128 v[214:217], v151 offset:39936
	global_load_lds_dwordx4 v[224:225], off
	v_lshl_add_u64 v[224:225], s[44:45], 0, v[130:131]
	s_mov_b32 m0, s56
	s_nop 0
	global_load_lds_dwordx4 v[224:225], off
	s_waitcnt vmcnt(8)
	s_waitcnt lgkmcnt(0)
	s_barrier
	s_setprio 1
	s_waitcnt lgkmcnt(0)
	v_mfma_f32_16x16x32_bf16 v[124:127], v[152:155], v[184:187], v[124:127]
	v_mfma_f32_16x16x32_bf16 v[120:123], v[160:163], v[184:187], v[120:123]
	v_mfma_f32_16x16x32_bf16 v[108:111], v[152:155], v[194:197], v[108:111]
	v_mfma_f32_16x16x32_bf16 v[104:107], v[160:163], v[194:197], v[104:107]
	v_mfma_f32_16x16x32_bf16 v[92:95], v[152:155], v[202:205], v[92:95]
	v_mfma_f32_16x16x32_bf16 v[88:91], v[160:163], v[202:205], v[88:91]
	v_mfma_f32_16x16x32_bf16 v[76:79], v[152:155], v[210:213], v[76:79]
	v_mfma_f32_16x16x32_bf16 v[72:75], v[160:163], v[210:213], v[72:75]
	v_mfma_f32_16x16x32_bf16 v[124:127], v[156:159], v[190:193], v[124:127]
	v_mfma_f32_16x16x32_bf16 v[120:123], v[164:167], v[190:193], v[120:123]
	v_mfma_f32_16x16x32_bf16 v[108:111], v[156:159], v[198:201], v[108:111]
	v_mfma_f32_16x16x32_bf16 v[104:107], v[164:167], v[198:201], v[104:107]
	v_mfma_f32_16x16x32_bf16 v[92:95], v[156:159], v[206:209], v[92:95]
	v_mfma_f32_16x16x32_bf16 v[88:91], v[164:167], v[206:209], v[88:91]
	v_mfma_f32_16x16x32_bf16 v[76:79], v[156:159], v[214:217], v[76:79]
	v_mfma_f32_16x16x32_bf16 v[72:75], v[164:167], v[214:217], v[72:75]
	s_setprio 0
	s_setprio 1
	v_mfma_f32_16x16x32_bf16 v[116:119], v[168:171], v[184:187], v[116:119]
	v_mfma_f32_16x16x32_bf16 v[112:115], v[176:179], v[184:187], v[112:115]
	v_mfma_f32_16x16x32_bf16 v[100:103], v[168:171], v[194:197], v[100:103]
	v_mfma_f32_16x16x32_bf16 v[96:99], v[176:179], v[194:197], v[96:99]
	v_mfma_f32_16x16x32_bf16 v[84:87], v[168:171], v[202:205], v[84:87]
	v_mfma_f32_16x16x32_bf16 v[80:83], v[176:179], v[202:205], v[80:83]
	v_mfma_f32_16x16x32_bf16 v[68:71], v[168:171], v[210:213], v[68:71]
	v_mfma_f32_16x16x32_bf16 v[64:67], v[176:179], v[210:213], v[64:67]
	v_mfma_f32_16x16x32_bf16 v[116:119], v[172:175], v[190:193], v[116:119]
	v_mfma_f32_16x16x32_bf16 v[112:115], v[180:183], v[190:193], v[112:115]
	v_mfma_f32_16x16x32_bf16 v[100:103], v[172:175], v[198:201], v[100:103]
	v_mfma_f32_16x16x32_bf16 v[96:99], v[180:183], v[198:201], v[96:99]
	v_mfma_f32_16x16x32_bf16 v[84:87], v[172:175], v[206:209], v[84:87]
	v_mfma_f32_16x16x32_bf16 v[80:83], v[180:183], v[206:209], v[80:83]
	v_mfma_f32_16x16x32_bf16 v[68:71], v[172:175], v[214:217], v[68:71]
	v_mfma_f32_16x16x32_bf16 v[64:67], v[180:183], v[214:217], v[64:67]
	s_setprio 0
	s_barrier
	s_add_i32 s44, s62, s51
	v_lshl_add_u64 v[144:145], v[144:145], 0, s[8:9]
	s_mov_b32 m0, s44
	ds_read_b128 v[184:187], v151 offset:49152
	ds_read_b128 v[190:193], v151 offset:50176
	ds_read_b128 v[194:197], v151 offset:51200
	ds_read_b128 v[198:201], v151 offset:52224
	ds_read_b128 v[202:205], v151 offset:53248
	ds_read_b128 v[206:209], v151 offset:54272
	ds_read_b128 v[210:213], v151 offset:55296
	ds_read_b128 v[214:217], v151 offset:56320
	global_load_lds_dwordx4 v[144:145], off
	s_add_i32 m0, s44, 0x2000
	s_add_u32 s42, s42, 0x40080
	v_lshl_add_u64 v[144:145], v[218:219], 0, s[8:9]
	s_addc_u32 s43, s43, 0
	s_add_i32 s44, s64, s51
	global_load_lds_dwordx4 v[144:145], off
	v_lshl_add_u64 v[144:145], s[42:43], 0, v[132:133]
	s_mov_b32 m0, s44
	s_nop 0
	global_load_lds_dwordx4 v[144:145], off
	v_lshl_add_u64 v[144:145], s[42:43], 0, v[128:129]
	s_add_i32 m0, s44, 0x2000
	s_nop 0
	global_load_lds_dwordx4 v[144:145], off
	v_lshl_add_u64 v[144:145], v[220:221], 0, s[8:9]
	s_mov_b32 m0, s57
	s_nop 0
	global_load_lds_dwordx4 v[144:145], off
	v_lshl_add_u64 v[144:145], v[222:223], 0, s[8:9]
	s_mov_b32 m0, s58
	s_nop 0
	global_load_lds_dwordx4 v[144:145], off
	s_waitcnt vmcnt(8)
	s_waitcnt lgkmcnt(0)
	s_barrier
	s_setprio 1
	s_waitcnt lgkmcnt(0)
	v_mfma_f32_16x16x32_bf16 v[60:63], v[152:155], v[184:187], v[60:63]
	v_mfma_f32_16x16x32_bf16 v[56:59], v[160:163], v[184:187], v[56:59]
	v_mfma_f32_16x16x32_bf16 v[44:47], v[152:155], v[194:197], v[44:47]
	v_mfma_f32_16x16x32_bf16 v[40:43], v[160:163], v[194:197], v[40:43]
	v_mfma_f32_16x16x32_bf16 v[28:31], v[152:155], v[202:205], v[28:31]
	v_mfma_f32_16x16x32_bf16 v[24:27], v[160:163], v[202:205], v[24:27]
	v_mfma_f32_16x16x32_bf16 v[12:15], v[152:155], v[210:213], v[12:15]
	v_mfma_f32_16x16x32_bf16 v[8:11], v[160:163], v[210:213], v[8:11]
	v_mfma_f32_16x16x32_bf16 v[60:63], v[156:159], v[190:193], v[60:63]
	v_mfma_f32_16x16x32_bf16 v[56:59], v[164:167], v[190:193], v[56:59]
	v_mfma_f32_16x16x32_bf16 v[44:47], v[156:159], v[198:201], v[44:47]
	v_mfma_f32_16x16x32_bf16 v[40:43], v[164:167], v[198:201], v[40:43]
	v_mfma_f32_16x16x32_bf16 v[28:31], v[156:159], v[206:209], v[28:31]
	v_mfma_f32_16x16x32_bf16 v[24:27], v[164:167], v[206:209], v[24:27]
	v_mfma_f32_16x16x32_bf16 v[12:15], v[156:159], v[214:217], v[12:15]
	v_mfma_f32_16x16x32_bf16 v[8:11], v[164:167], v[214:217], v[8:11]
	s_setprio 0
	s_setprio 1
	v_mfma_f32_16x16x32_bf16 v[52:55], v[168:171], v[184:187], v[52:55]
	v_mfma_f32_16x16x32_bf16 v[48:51], v[176:179], v[184:187], v[48:51]
	v_mfma_f32_16x16x32_bf16 v[36:39], v[168:171], v[194:197], v[36:39]
	v_mfma_f32_16x16x32_bf16 v[32:35], v[176:179], v[194:197], v[32:35]
	v_mfma_f32_16x16x32_bf16 v[20:23], v[168:171], v[202:205], v[20:23]
	v_mfma_f32_16x16x32_bf16 v[16:19], v[176:179], v[202:205], v[16:19]
	v_mfma_f32_16x16x32_bf16 v[4:7], v[168:171], v[210:213], v[4:7]
	v_mfma_f32_16x16x32_bf16 v[0:3], v[176:179], v[210:213], v[0:3]
	v_mfma_f32_16x16x32_bf16 v[52:55], v[172:175], v[190:193], v[52:55]
	v_mfma_f32_16x16x32_bf16 v[48:51], v[180:183], v[190:193], v[48:51]
	v_mfma_f32_16x16x32_bf16 v[36:39], v[172:175], v[198:201], v[36:39]
	v_mfma_f32_16x16x32_bf16 v[32:35], v[180:183], v[198:201], v[32:35]
	v_mfma_f32_16x16x32_bf16 v[20:23], v[172:175], v[206:209], v[20:23]
	v_mfma_f32_16x16x32_bf16 v[16:19], v[180:183], v[206:209], v[16:19]
	v_mfma_f32_16x16x32_bf16 v[4:7], v[172:175], v[214:217], v[4:7]
	v_mfma_f32_16x16x32_bf16 v[0:3], v[180:183], v[214:217], v[0:3]
	s_add_i32 s75, s75, 2
	s_add_u32 s40, s40, 0x100
	s_addc_u32 s41, s41, 0
	s_add_u32 s73, s73, 0x100
	s_addc_u32 s74, s74, 0
	s_cmp_gt_u32 s75, 13
	s_setprio 0
	s_barrier
	s_cbranch_scc0 .LBB0_1303
	s_and_b64 vcc, exec, s[10:11]
	s_cbranch_vccz .LBB0_1306
	s_barrier
